# v53 + GDN chunk-local forward substitution re-emitted by hand: plain f32 FMAs, four rows in flight, M rows through a register ring with counted lgkmcnt (no dependent-chain stalls)
# speedup vs baseline: 1.0099x; 1.0099x over previous
; #define LAS __attribute__((address_space(3)))
; __device__ __forceinline__ void gdn_local_unit(LAS unsigned char* lds, const GdnP& P, int unit, const int tid, const int pf) {
;     ...
;             for (int t = 0; t < 64; ++t) sol2[t >> 1][t & 1] = Ks[t * 132 + col - 128] * rk[t] * beta[t] * eG[t];
;         }
; #pragma unroll
;         for (int c = 1; c < 64; ++c) { f32x2 sp = (f32x2){sol2[c >> 1][c & 1], 0.f};
; #pragma unroll
;             for (int jb = 0; jb <= (c - 1) / 4; ++jb) { const f32x4 m4 = *(const LAS f32x4*)(Ms + c * 64 + 4 * jb);
;                 sp -= (f32x2){m4.x, m4.y} * sol2[2 * jb]; sp -= (f32x2){m4.z, m4.w} * sol2[2 * jb + 1]; }
;             sol2[c >> 1][c & 1] = sp.x + sp.y; }
.LBB0_1025:
	s_or_b64 exec, exec, s[0:1]
	v_add_u32_e32 v3, v130, v3
	ds_read_b32 v3, v3
	ds_read_b128 v[142:145], v109 offset:256
	ds_read_b128 v[146:149], v109 offset:512
	ds_read_b128 v[150:153], v109 offset:768
	ds_read_b128 v[154:157], v109 offset:1024
	ds_read_b128 v[158:161], v109 offset:1280
	ds_read_b128 v[220:223], v109 offset:1536
	ds_read_b128 v[230:233], v109 offset:1792
	ds_read_b128 v[234:237], v109 offset:1296
	s_waitcnt lgkmcnt(5)
	v_mul_f32_e32 v3, v5, v3
	v_fma_f32 v1, -v142, v0, v1
	ds_read_b128 v[142:145], v109 offset:2048
	v_fma_f32 v8, -v146, v0, v8
	v_fma_f32 v9, -v150, v0, v9
	v_fma_f32 v8, -v147, v1, v8
	ds_read_b128 v[146:149], v109 offset:2304
	v_fma_f32 v9, -v151, v1, v9
	v_fma_f32 v9, -v152, v8, v9
	ds_read_b128 v[150:153], v109 offset:2560
	s_waitcnt lgkmcnt(4)
	v_fma_f32 v20, -v154, v0, v14
	v_fma_f32 v21, -v158, v0, v15
	v_fma_f32 v24, -v220, v0, v18
	v_fma_f32 v25, -v230, v0, v19
	v_fma_f32 v20, -v155, v1, v20
	v_fma_f32 v21, -v159, v1, v21
	v_fma_f32 v24, -v221, v1, v24
	v_fma_f32 v25, -v231, v1, v25
	v_fma_f32 v20, -v156, v8, v20
	v_fma_f32 v21, -v160, v8, v21
	v_fma_f32 v24, -v222, v8, v24
	v_fma_f32 v25, -v232, v8, v25
	v_fma_f32 v14, -v157, v9, v20
	ds_read_b128 v[154:157], v109 offset:1552
	v_fma_f32 v21, -v161, v9, v21
	ds_read_b128 v[158:161], v109 offset:2816
	v_fma_f32 v24, -v223, v9, v24
	ds_read_b128 v[220:223], v109 offset:1808
	v_fma_f32 v25, -v233, v9, v25
	ds_read_b128 v[230:233], v109 offset:2064
	s_waitcnt lgkmcnt(4)
	v_fma_f32 v15, -v234, v14, v21
	ds_read_b128 v[234:237], v109 offset:2320
	v_fma_f32 v10, -v142, v0, v22
	v_fma_f32 v11, -v146, v0, v23
	v_fma_f32 v16, -v150, v0, v26
	s_waitcnt lgkmcnt(3)
	v_fma_f32 v24, -v154, v14, v24
	v_fma_f32 v17, -v158, v0, v27
	v_fma_f32 v10, -v143, v1, v10
	v_fma_f32 v11, -v147, v1, v11
	s_waitcnt lgkmcnt(2)
	v_fma_f32 v25, -v220, v14, v25
	v_fma_f32 v16, -v151, v1, v16
	v_fma_f32 v17, -v159, v1, v17
	v_fma_f32 v10, -v144, v8, v10
	v_fma_f32 v18, -v155, v15, v24
	ds_read_b128 v[154:157], v109 offset:2576
	v_fma_f32 v11, -v148, v8, v11
	v_fma_f32 v16, -v152, v8, v16
	v_fma_f32 v17, -v160, v8, v17
	v_fma_f32 v25, -v221, v15, v25
	v_fma_f32 v10, -v145, v9, v10
	ds_read_b128 v[142:145], v109 offset:2832
	v_fma_f32 v11, -v149, v9, v11
	ds_read_b128 v[146:149], v109 offset:2336
	v_fma_f32 v16, -v153, v9, v16
	ds_read_b128 v[150:153], v109 offset:3072
	v_fma_f32 v19, -v222, v18, v25
	ds_read_b128 v[220:223], v109 offset:3328
	v_fma_f32 v17, -v161, v9, v17
	ds_read_b128 v[158:161], v109 offset:3584
	s_waitcnt lgkmcnt(4)
	v_fma_f32 v10, -v230, v14, v10
	v_fma_f32 v11, -v234, v14, v11
	v_fma_f32 v16, -v154, v14, v16
	v_fma_f32 v17, -v142, v14, v17
	v_fma_f32 v10, -v231, v15, v10
	v_fma_f32 v11, -v235, v15, v11
	v_fma_f32 v16, -v155, v15, v16
	v_fma_f32 v17, -v143, v15, v17
	v_fma_f32 v10, -v232, v18, v10
	v_fma_f32 v11, -v236, v18, v11
	v_fma_f32 v16, -v156, v18, v16
	v_fma_f32 v17, -v144, v18, v17
	v_fma_f32 v22, -v233, v19, v10
	ds_read_b128 v[230:233], v109 offset:2592
	v_fma_f32 v11, -v237, v19, v11
	ds_read_b128 v[234:237], v109 offset:3840
	v_fma_f32 v16, -v157, v19, v16
	ds_read_b128 v[154:157], v109 offset:2848
	v_fma_f32 v17, -v145, v19, v17
	ds_read_b128 v[142:145], v109 offset:3088
	s_waitcnt lgkmcnt(4)
	v_fma_f32 v23, -v146, v22, v11
	ds_read_b128 v[146:149], v109 offset:3344
	v_fma_f32 v20, -v150, v0, v30
	v_fma_f32 v21, -v220, v0, v31
	v_fma_f32 v24, -v158, v0, v36
	s_waitcnt lgkmcnt(3)
	v_fma_f32 v16, -v230, v22, v16
	v_fma_f32 v25, -v234, v0, v37
	v_fma_f32 v20, -v151, v1, v20
	v_fma_f32 v21, -v221, v1, v21
	s_waitcnt lgkmcnt(2)
	v_fma_f32 v17, -v154, v22, v17
	v_fma_f32 v24, -v159, v1, v24
	v_fma_f32 v25, -v235, v1, v25
	v_fma_f32 v20, -v152, v8, v20
	v_fma_f32 v26, -v231, v23, v16
	ds_read_b128 v[230:233], v109 offset:3600
	v_fma_f32 v21, -v222, v8, v21
	v_fma_f32 v24, -v160, v8, v24
	v_fma_f32 v25, -v236, v8, v25
	v_fma_f32 v17, -v155, v23, v17
	v_fma_f32 v20, -v153, v9, v20
	ds_read_b128 v[150:153], v109 offset:3856
	v_fma_f32 v21, -v223, v9, v21
	ds_read_b128 v[220:223], v109 offset:3104
	v_fma_f32 v24, -v161, v9, v24
	ds_read_b128 v[158:161], v109 offset:3360
	v_fma_f32 v27, -v156, v26, v17
	ds_read_b128 v[154:157], v109 offset:3616
	v_fma_f32 v25, -v237, v9, v25
	ds_read_b128 v[234:237], v109 offset:3872
	s_waitcnt lgkmcnt(4)
	v_fma_f32 v20, -v142, v14, v20
	v_fma_f32 v21, -v146, v14, v21
	v_fma_f32 v24, -v230, v14, v24
	v_fma_f32 v25, -v150, v14, v25
	v_fma_f32 v20, -v143, v15, v20
	v_fma_f32 v21, -v147, v15, v21
	v_fma_f32 v24, -v231, v15, v24
	v_fma_f32 v25, -v151, v15, v25
	v_fma_f32 v20, -v144, v18, v20
	v_fma_f32 v21, -v148, v18, v21
	v_fma_f32 v24, -v232, v18, v24
	v_fma_f32 v25, -v152, v18, v25
	v_fma_f32 v20, -v145, v19, v20
	ds_read_b128 v[142:145], v109 offset:3376
	v_fma_f32 v21, -v149, v19, v21
	ds_read_b128 v[146:149], v109 offset:4096
	v_fma_f32 v24, -v233, v19, v24
	ds_read_b128 v[230:233], v109 offset:4352
	v_fma_f32 v25, -v153, v19, v25
	ds_read_b128 v[150:153], v109 offset:4608
	s_waitcnt lgkmcnt(4)
	v_fma_f32 v20, -v220, v22, v20
	v_fma_f32 v21, -v158, v22, v21
	v_fma_f32 v24, -v154, v22, v24
	v_fma_f32 v25, -v234, v22, v25
	v_fma_f32 v20, -v221, v23, v20
	v_fma_f32 v21, -v159, v23, v21
	v_fma_f32 v24, -v155, v23, v24
	v_fma_f32 v25, -v235, v23, v25
	v_fma_f32 v20, -v222, v26, v20
	v_fma_f32 v21, -v160, v26, v21
	v_fma_f32 v24, -v156, v26, v24
	v_fma_f32 v25, -v236, v26, v25
	v_fma_f32 v30, -v223, v27, v20
	ds_read_b128 v[220:223], v109 offset:3632
	v_fma_f32 v21, -v161, v27, v21
	ds_read_b128 v[158:161], v109 offset:4864
	v_fma_f32 v24, -v157, v27, v24
	ds_read_b128 v[154:157], v109 offset:3888
	v_fma_f32 v25, -v237, v27, v25
	ds_read_b128 v[234:237], v109 offset:4112
	s_waitcnt lgkmcnt(4)
; #define LAS __attribute__((address_space(3)))
; __device__ __forceinline__ void gdn_local_unit(LAS unsigned char* lds, const GdnP& P, int unit, const int tid, const int pf) {
;     ...
;         for (int c = 1; c < 64; ++c) { f32x2 sp = (f32x2){sol2[c >> 1][c & 1], 0.f};
; #pragma unroll
;             for (int jb = 0; jb <= (c - 1) / 4; ++jb) { const f32x4 m4 = *(const LAS f32x4*)(Ms + c * 64 + 4 * jb);
;                 sp -= (f32x2){m4.x, m4.y} * sol2[2 * jb]; sp -= (f32x2){m4.z, m4.w} * sol2[2 * jb + 1]; }
;             sol2[c >> 1][c & 1] = sp.x + sp.y; }
	v_fma_f32 v31, -v142, v30, v21
	ds_read_b128 v[142:145], v109 offset:4368
	v_fma_f32 v10, -v146, v0, v40
	v_fma_f32 v11, -v230, v0, v41
	v_fma_f32 v16, -v150, v0, v44
	s_waitcnt lgkmcnt(3)
	v_fma_f32 v24, -v220, v30, v24
	v_fma_f32 v17, -v158, v0, v45
	v_fma_f32 v10, -v147, v1, v10
	v_fma_f32 v11, -v231, v1, v11
	s_waitcnt lgkmcnt(2)
	v_fma_f32 v25, -v154, v30, v25
	v_fma_f32 v16, -v151, v1, v16
	v_fma_f32 v17, -v159, v1, v17
	v_fma_f32 v10, -v148, v8, v10
	v_fma_f32 v36, -v221, v31, v24
	ds_read_b128 v[220:223], v109 offset:4624
	v_fma_f32 v11, -v232, v8, v11
	v_fma_f32 v16, -v152, v8, v16
	v_fma_f32 v17, -v160, v8, v17
	v_fma_f32 v25, -v155, v31, v25
	v_fma_f32 v10, -v149, v9, v10
	ds_read_b128 v[146:149], v109 offset:4880
	v_fma_f32 v11, -v233, v9, v11
	ds_read_b128 v[230:233], v109 offset:4128
	v_fma_f32 v16, -v153, v9, v16
	ds_read_b128 v[150:153], v109 offset:4384
	v_fma_f32 v37, -v156, v36, v25
	ds_read_b128 v[154:157], v109 offset:4640
	v_fma_f32 v17, -v161, v9, v17
	ds_read_b128 v[158:161], v109 offset:4896
	s_waitcnt lgkmcnt(4)
	v_fma_f32 v10, -v234, v14, v10
	v_fma_f32 v11, -v142, v14, v11
	v_fma_f32 v16, -v220, v14, v16
	v_fma_f32 v17, -v146, v14, v17
	v_fma_f32 v10, -v235, v15, v10
	v_fma_f32 v11, -v143, v15, v11
	v_fma_f32 v16, -v221, v15, v16
	v_fma_f32 v17, -v147, v15, v17
	v_fma_f32 v10, -v236, v18, v10
	v_fma_f32 v11, -v144, v18, v11
	v_fma_f32 v16, -v222, v18, v16
	v_fma_f32 v17, -v148, v18, v17
	v_fma_f32 v10, -v237, v19, v10
	ds_read_b128 v[234:237], v109 offset:4144
	v_fma_f32 v11, -v145, v19, v11
	ds_read_b128 v[142:145], v109 offset:4400
	v_fma_f32 v16, -v223, v19, v16
	ds_read_b128 v[220:223], v109 offset:4656
	v_fma_f32 v17, -v149, v19, v17
	ds_read_b128 v[146:149], v109 offset:4912
	s_waitcnt lgkmcnt(4)
	v_fma_f32 v10, -v230, v22, v10
	v_fma_f32 v11, -v150, v22, v11
	v_fma_f32 v16, -v154, v22, v16
	v_fma_f32 v17, -v158, v22, v17
	v_fma_f32 v10, -v231, v23, v10
	v_fma_f32 v11, -v151, v23, v11
	v_fma_f32 v16, -v155, v23, v16
	v_fma_f32 v17, -v159, v23, v17
	v_fma_f32 v10, -v232, v26, v10
	v_fma_f32 v11, -v152, v26, v11
	v_fma_f32 v16, -v156, v26, v16
	v_fma_f32 v17, -v160, v26, v17
	v_fma_f32 v10, -v233, v27, v10
	ds_read_b128 v[230:233], v109 offset:4416
	v_fma_f32 v11, -v153, v27, v11
	ds_read_b128 v[150:153], v109 offset:5120
	v_fma_f32 v16, -v157, v27, v16
	ds_read_b128 v[154:157], v109 offset:5376
	v_fma_f32 v17, -v161, v27, v17
	ds_read_b128 v[158:161], v109 offset:5632
	s_waitcnt lgkmcnt(4)
	v_fma_f32 v10, -v234, v30, v10
	v_fma_f32 v11, -v142, v30, v11
	v_fma_f32 v16, -v220, v30, v16
	v_fma_f32 v17, -v146, v30, v17
	v_fma_f32 v10, -v235, v31, v10
	v_fma_f32 v11, -v143, v31, v11
	v_fma_f32 v16, -v221, v31, v16
	v_fma_f32 v17, -v147, v31, v17
	v_fma_f32 v10, -v236, v36, v10
	v_fma_f32 v11, -v144, v36, v11
	v_fma_f32 v16, -v222, v36, v16
	v_fma_f32 v17, -v148, v36, v17
	v_fma_f32 v40, -v237, v37, v10
	ds_read_b128 v[234:237], v109 offset:4672
	v_fma_f32 v11, -v145, v37, v11
	ds_read_b128 v[142:145], v109 offset:5888
	v_fma_f32 v16, -v223, v37, v16
	ds_read_b128 v[220:223], v109 offset:4928
	v_fma_f32 v17, -v149, v37, v17
	ds_read_b128 v[146:149], v109 offset:5136
	s_waitcnt lgkmcnt(4)
	v_fma_f32 v41, -v230, v40, v11
	ds_read_b128 v[230:233], v109 offset:5392
	v_fma_f32 v20, -v150, v0, v50
	v_fma_f32 v21, -v154, v0, v51
	v_fma_f32 v24, -v158, v0, v54
	s_waitcnt lgkmcnt(3)
	v_fma_f32 v16, -v234, v40, v16
	v_fma_f32 v25, -v142, v0, v55
	v_fma_f32 v20, -v151, v1, v20
	v_fma_f32 v21, -v155, v1, v21
	s_waitcnt lgkmcnt(2)
	v_fma_f32 v17, -v220, v40, v17
	v_fma_f32 v24, -v159, v1, v24
	v_fma_f32 v25, -v143, v1, v25
	v_fma_f32 v20, -v152, v8, v20
	v_fma_f32 v44, -v235, v41, v16
	ds_read_b128 v[234:237], v109 offset:5648
	v_fma_f32 v21, -v156, v8, v21
	v_fma_f32 v24, -v160, v8, v24
	v_fma_f32 v25, -v144, v8, v25
	v_fma_f32 v17, -v221, v41, v17
	v_fma_f32 v20, -v153, v9, v20
	ds_read_b128 v[150:153], v109 offset:5904
	v_fma_f32 v21, -v157, v9, v21
	ds_read_b128 v[154:157], v109 offset:5152
	v_fma_f32 v24, -v161, v9, v24
	ds_read_b128 v[158:161], v109 offset:5408
	v_fma_f32 v45, -v222, v44, v17
	ds_read_b128 v[220:223], v109 offset:5664
	v_fma_f32 v25, -v145, v9, v25
	ds_read_b128 v[142:145], v109 offset:5920
	s_waitcnt lgkmcnt(4)
	v_fma_f32 v20, -v146, v14, v20
	v_fma_f32 v21, -v230, v14, v21
	v_fma_f32 v24, -v234, v14, v24
	v_fma_f32 v25, -v150, v14, v25
	v_fma_f32 v20, -v147, v15, v20
	v_fma_f32 v21, -v231, v15, v21
	v_fma_f32 v24, -v235, v15, v24
	v_fma_f32 v25, -v151, v15, v25
	v_fma_f32 v20, -v148, v18, v20
	v_fma_f32 v21, -v232, v18, v21
	v_fma_f32 v24, -v236, v18, v24
	v_fma_f32 v25, -v152, v18, v25
	v_fma_f32 v20, -v149, v19, v20
	ds_read_b128 v[146:149], v109 offset:5168
	v_fma_f32 v21, -v233, v19, v21
	ds_read_b128 v[230:233], v109 offset:5424
	v_fma_f32 v24, -v237, v19, v24
	ds_read_b128 v[234:237], v109 offset:5680
	v_fma_f32 v25, -v153, v19, v25
	ds_read_b128 v[150:153], v109 offset:5936
	s_waitcnt lgkmcnt(4)
	v_fma_f32 v20, -v154, v22, v20
	v_fma_f32 v21, -v158, v22, v21
	v_fma_f32 v24, -v220, v22, v24
	v_fma_f32 v25, -v142, v22, v25
	v_fma_f32 v20, -v155, v23, v20
	v_fma_f32 v21, -v159, v23, v21
	v_fma_f32 v24, -v221, v23, v24
	v_fma_f32 v25, -v143, v23, v25
	v_fma_f32 v20, -v156, v26, v20
	v_fma_f32 v21, -v160, v26, v21
	v_fma_f32 v24, -v222, v26, v24
	v_fma_f32 v25, -v144, v26, v25
	v_fma_f32 v20, -v157, v27, v20
	ds_read_b128 v[154:157], v109 offset:5184
	v_fma_f32 v21, -v161, v27, v21
	ds_read_b128 v[158:161], v109 offset:5440
	v_fma_f32 v24, -v223, v27, v24
	ds_read_b128 v[220:223], v109 offset:5696
	v_fma_f32 v25, -v145, v27, v25
	ds_read_b128 v[142:145], v109 offset:5952
	s_waitcnt lgkmcnt(4)
; #define LAS __attribute__((address_space(3)))
; __device__ __forceinline__ void gdn_local_unit(LAS unsigned char* lds, const GdnP& P, int unit, const int tid, const int pf) {
;     ...
;         for (int c = 1; c < 64; ++c) { f32x2 sp = (f32x2){sol2[c >> 1][c & 1], 0.f};
; #pragma unroll
;             for (int jb = 0; jb <= (c - 1) / 4; ++jb) { const f32x4 m4 = *(const LAS f32x4*)(Ms + c * 64 + 4 * jb);
;                 sp -= (f32x2){m4.x, m4.y} * sol2[2 * jb]; sp -= (f32x2){m4.z, m4.w} * sol2[2 * jb + 1]; }
;             sol2[c >> 1][c & 1] = sp.x + sp.y; }
	v_fma_f32 v20, -v146, v30, v20
	v_fma_f32 v21, -v230, v30, v21
	v_fma_f32 v24, -v234, v30, v24
	v_fma_f32 v25, -v150, v30, v25
	v_fma_f32 v20, -v147, v31, v20
	v_fma_f32 v21, -v231, v31, v21
	v_fma_f32 v24, -v235, v31, v24
	v_fma_f32 v25, -v151, v31, v25
	v_fma_f32 v20, -v148, v36, v20
	v_fma_f32 v21, -v232, v36, v21
	v_fma_f32 v24, -v236, v36, v24
	v_fma_f32 v25, -v152, v36, v25
	v_fma_f32 v20, -v149, v37, v20
	ds_read_b128 v[146:149], v109 offset:5456
	v_fma_f32 v21, -v233, v37, v21
	ds_read_b128 v[230:233], v109 offset:6144
	v_fma_f32 v24, -v237, v37, v24
	ds_read_b128 v[234:237], v109 offset:6400
	v_fma_f32 v25, -v153, v37, v25
	ds_read_b128 v[150:153], v109 offset:6656
	s_waitcnt lgkmcnt(4)
	v_fma_f32 v20, -v154, v40, v20
	v_fma_f32 v21, -v158, v40, v21
	v_fma_f32 v24, -v220, v40, v24
	v_fma_f32 v25, -v142, v40, v25
	v_fma_f32 v20, -v155, v41, v20
	v_fma_f32 v21, -v159, v41, v21
	v_fma_f32 v24, -v221, v41, v24
	v_fma_f32 v25, -v143, v41, v25
	v_fma_f32 v20, -v156, v44, v20
	v_fma_f32 v21, -v160, v44, v21
	v_fma_f32 v24, -v222, v44, v24
	v_fma_f32 v25, -v144, v44, v25
	v_fma_f32 v50, -v157, v45, v20
	ds_read_b128 v[154:157], v109 offset:5712
	v_fma_f32 v21, -v161, v45, v21
	ds_read_b128 v[158:161], v109 offset:6912
	v_fma_f32 v24, -v223, v45, v24
	ds_read_b128 v[220:223], v109 offset:5968
	v_fma_f32 v25, -v145, v45, v25
	ds_read_b128 v[142:145], v109 offset:6160
	s_waitcnt lgkmcnt(4)
	v_fma_f32 v51, -v146, v50, v21
	ds_read_b128 v[146:149], v109 offset:6416
	v_fma_f32 v10, -v230, v0, v60
	v_fma_f32 v11, -v234, v0, v61
	v_fma_f32 v16, -v150, v0, v64
	s_waitcnt lgkmcnt(3)
	v_fma_f32 v24, -v154, v50, v24
	v_fma_f32 v17, -v158, v0, v65
	v_fma_f32 v10, -v231, v1, v10
	v_fma_f32 v11, -v235, v1, v11
	s_waitcnt lgkmcnt(2)
	v_fma_f32 v25, -v220, v50, v25
	v_fma_f32 v16, -v151, v1, v16
	v_fma_f32 v17, -v159, v1, v17
	v_fma_f32 v10, -v232, v8, v10
	v_fma_f32 v54, -v155, v51, v24
	ds_read_b128 v[154:157], v109 offset:6672
	v_fma_f32 v11, -v236, v8, v11
	v_fma_f32 v16, -v152, v8, v16
	v_fma_f32 v17, -v160, v8, v17
	v_fma_f32 v25, -v221, v51, v25
	v_fma_f32 v10, -v233, v9, v10
	ds_read_b128 v[230:233], v109 offset:6928
	v_fma_f32 v11, -v237, v9, v11
	ds_read_b128 v[234:237], v109 offset:6176
	v_fma_f32 v16, -v153, v9, v16
	ds_read_b128 v[150:153], v109 offset:6432
	v_fma_f32 v55, -v222, v54, v25
	ds_read_b128 v[220:223], v109 offset:6688
	v_fma_f32 v17, -v161, v9, v17
	ds_read_b128 v[158:161], v109 offset:6944
	s_waitcnt lgkmcnt(4)
	v_fma_f32 v10, -v142, v14, v10
	v_fma_f32 v11, -v146, v14, v11
	v_fma_f32 v16, -v154, v14, v16
	v_fma_f32 v17, -v230, v14, v17
	v_fma_f32 v10, -v143, v15, v10
	v_fma_f32 v11, -v147, v15, v11
	v_fma_f32 v16, -v155, v15, v16
	v_fma_f32 v17, -v231, v15, v17
	v_fma_f32 v10, -v144, v18, v10
	v_fma_f32 v11, -v148, v18, v11
	v_fma_f32 v16, -v156, v18, v16
	v_fma_f32 v17, -v232, v18, v17
	v_fma_f32 v10, -v145, v19, v10
	ds_read_b128 v[142:145], v109 offset:6192
	v_fma_f32 v11, -v149, v19, v11
	ds_read_b128 v[146:149], v109 offset:6448
	v_fma_f32 v16, -v157, v19, v16
	ds_read_b128 v[154:157], v109 offset:6704
	v_fma_f32 v17, -v233, v19, v17
	ds_read_b128 v[230:233], v109 offset:6960
	s_waitcnt lgkmcnt(4)
	v_fma_f32 v10, -v234, v22, v10
	v_fma_f32 v11, -v150, v22, v11
	v_fma_f32 v16, -v220, v22, v16
	v_fma_f32 v17, -v158, v22, v17
	v_fma_f32 v10, -v235, v23, v10
	v_fma_f32 v11, -v151, v23, v11
	v_fma_f32 v16, -v221, v23, v16
	v_fma_f32 v17, -v159, v23, v17
	v_fma_f32 v10, -v236, v26, v10
	v_fma_f32 v11, -v152, v26, v11
	v_fma_f32 v16, -v222, v26, v16
	v_fma_f32 v17, -v160, v26, v17
	v_fma_f32 v10, -v237, v27, v10
	ds_read_b128 v[234:237], v109 offset:6208
	v_fma_f32 v11, -v153, v27, v11
	ds_read_b128 v[150:153], v109 offset:6464
	v_fma_f32 v16, -v223, v27, v16
	ds_read_b128 v[220:223], v109 offset:6720
	v_fma_f32 v17, -v161, v27, v17
	ds_read_b128 v[158:161], v109 offset:6976
	s_waitcnt lgkmcnt(4)
	v_fma_f32 v10, -v142, v30, v10
	v_fma_f32 v11, -v146, v30, v11
	v_fma_f32 v16, -v154, v30, v16
	v_fma_f32 v17, -v230, v30, v17
	v_fma_f32 v10, -v143, v31, v10
	v_fma_f32 v11, -v147, v31, v11
	v_fma_f32 v16, -v155, v31, v16
	v_fma_f32 v17, -v231, v31, v17
	v_fma_f32 v10, -v144, v36, v10
	v_fma_f32 v11, -v148, v36, v11
	v_fma_f32 v16, -v156, v36, v16
	v_fma_f32 v17, -v232, v36, v17
	v_fma_f32 v10, -v145, v37, v10
	ds_read_b128 v[142:145], v109 offset:6224
	v_fma_f32 v11, -v149, v37, v11
	ds_read_b128 v[146:149], v109 offset:6480
	v_fma_f32 v16, -v157, v37, v16
	ds_read_b128 v[154:157], v109 offset:6736
	v_fma_f32 v17, -v233, v37, v17
	ds_read_b128 v[230:233], v109 offset:6992
	s_waitcnt lgkmcnt(4)
	v_fma_f32 v10, -v234, v40, v10
	v_fma_f32 v11, -v150, v40, v11
	v_fma_f32 v16, -v220, v40, v16
	v_fma_f32 v17, -v158, v40, v17
	v_fma_f32 v10, -v235, v41, v10
	v_fma_f32 v11, -v151, v41, v11
	v_fma_f32 v16, -v221, v41, v16
	v_fma_f32 v17, -v159, v41, v17
	v_fma_f32 v10, -v236, v44, v10
	v_fma_f32 v11, -v152, v44, v11
	v_fma_f32 v16, -v222, v44, v16
	v_fma_f32 v17, -v160, v44, v17
	v_fma_f32 v10, -v237, v45, v10
	ds_read_b128 v[234:237], v109 offset:6496
	v_fma_f32 v11, -v153, v45, v11
	ds_read_b128 v[150:153], v109 offset:7168
	v_fma_f32 v16, -v223, v45, v16
	ds_read_b128 v[220:223], v109 offset:7424
	v_fma_f32 v17, -v161, v45, v17
	ds_read_b128 v[158:161], v109 offset:7680
	s_waitcnt lgkmcnt(4)
; #define LAS __attribute__((address_space(3)))
; __device__ __forceinline__ void gdn_local_unit(LAS unsigned char* lds, const GdnP& P, int unit, const int tid, const int pf) {
;     ...
;         for (int c = 1; c < 64; ++c) { f32x2 sp = (f32x2){sol2[c >> 1][c & 1], 0.f};
; #pragma unroll
;             for (int jb = 0; jb <= (c - 1) / 4; ++jb) { const f32x4 m4 = *(const LAS f32x4*)(Ms + c * 64 + 4 * jb);
;                 sp -= (f32x2){m4.x, m4.y} * sol2[2 * jb]; sp -= (f32x2){m4.z, m4.w} * sol2[2 * jb + 1]; }
;             sol2[c >> 1][c & 1] = sp.x + sp.y; }
	v_fma_f32 v10, -v142, v50, v10
	v_fma_f32 v11, -v146, v50, v11
	v_fma_f32 v16, -v154, v50, v16
	v_fma_f32 v17, -v230, v50, v17
	v_fma_f32 v10, -v143, v51, v10
	v_fma_f32 v11, -v147, v51, v11
	v_fma_f32 v16, -v155, v51, v16
	v_fma_f32 v17, -v231, v51, v17
	v_fma_f32 v10, -v144, v54, v10
	v_fma_f32 v11, -v148, v54, v11
	v_fma_f32 v16, -v156, v54, v16
	v_fma_f32 v17, -v232, v54, v17
	v_fma_f32 v60, -v145, v55, v10
	ds_read_b128 v[142:145], v109 offset:6752
	v_fma_f32 v11, -v149, v55, v11
	ds_read_b128 v[146:149], v109 offset:7936
	v_fma_f32 v16, -v157, v55, v16
	ds_read_b128 v[154:157], v109 offset:7008
	v_fma_f32 v17, -v233, v55, v17
	ds_read_b128 v[230:233], v109 offset:7184
	s_waitcnt lgkmcnt(4)
	v_fma_f32 v61, -v234, v60, v11
	ds_read_b128 v[234:237], v109 offset:7440
	v_fma_f32 v20, -v150, v0, v70
	v_fma_f32 v21, -v220, v0, v71
	v_fma_f32 v24, -v158, v0, v112
	s_waitcnt lgkmcnt(3)
	v_fma_f32 v16, -v142, v60, v16
	v_fma_f32 v25, -v146, v0, v113
	v_fma_f32 v20, -v151, v1, v20
	v_fma_f32 v21, -v221, v1, v21
	s_waitcnt lgkmcnt(2)
	v_fma_f32 v17, -v154, v60, v17
	v_fma_f32 v24, -v159, v1, v24
	v_fma_f32 v25, -v147, v1, v25
	v_fma_f32 v20, -v152, v8, v20
	v_fma_f32 v64, -v143, v61, v16
	ds_read_b128 v[142:145], v109 offset:7696
	v_fma_f32 v21, -v222, v8, v21
	v_fma_f32 v24, -v160, v8, v24
	v_fma_f32 v25, -v148, v8, v25
	v_fma_f32 v17, -v155, v61, v17
	v_fma_f32 v20, -v153, v9, v20
	ds_read_b128 v[150:153], v109 offset:7952
	v_fma_f32 v21, -v223, v9, v21
	ds_read_b128 v[220:223], v109 offset:7200
	v_fma_f32 v24, -v161, v9, v24
	ds_read_b128 v[158:161], v109 offset:7456
	v_fma_f32 v65, -v156, v64, v17
	ds_read_b128 v[154:157], v109 offset:7712
	v_fma_f32 v25, -v149, v9, v25
	ds_read_b128 v[146:149], v109 offset:7968
	s_waitcnt lgkmcnt(4)
	v_fma_f32 v20, -v230, v14, v20
	v_fma_f32 v21, -v234, v14, v21
	v_fma_f32 v24, -v142, v14, v24
	v_fma_f32 v25, -v150, v14, v25
	v_fma_f32 v20, -v231, v15, v20
	v_fma_f32 v21, -v235, v15, v21
	v_fma_f32 v24, -v143, v15, v24
	v_fma_f32 v25, -v151, v15, v25
	v_fma_f32 v20, -v232, v18, v20
	v_fma_f32 v21, -v236, v18, v21
	v_fma_f32 v24, -v144, v18, v24
	v_fma_f32 v25, -v152, v18, v25
	v_fma_f32 v20, -v233, v19, v20
	ds_read_b128 v[230:233], v109 offset:7216
	v_fma_f32 v21, -v237, v19, v21
	ds_read_b128 v[234:237], v109 offset:7472
	v_fma_f32 v24, -v145, v19, v24
	ds_read_b128 v[142:145], v109 offset:7728
	v_fma_f32 v25, -v153, v19, v25
	ds_read_b128 v[150:153], v109 offset:7984
	s_waitcnt lgkmcnt(4)
	v_fma_f32 v20, -v220, v22, v20
	v_fma_f32 v21, -v158, v22, v21
	v_fma_f32 v24, -v154, v22, v24
	v_fma_f32 v25, -v146, v22, v25
	v_fma_f32 v20, -v221, v23, v20
	v_fma_f32 v21, -v159, v23, v21
	v_fma_f32 v24, -v155, v23, v24
	v_fma_f32 v25, -v147, v23, v25
	v_fma_f32 v20, -v222, v26, v20
	v_fma_f32 v21, -v160, v26, v21
	v_fma_f32 v24, -v156, v26, v24
	v_fma_f32 v25, -v148, v26, v25
	v_fma_f32 v20, -v223, v27, v20
	ds_read_b128 v[220:223], v109 offset:7232
	v_fma_f32 v21, -v161, v27, v21
	ds_read_b128 v[158:161], v109 offset:7488
	v_fma_f32 v24, -v157, v27, v24
	ds_read_b128 v[154:157], v109 offset:7744
	v_fma_f32 v25, -v149, v27, v25
	ds_read_b128 v[146:149], v109 offset:8000
	s_waitcnt lgkmcnt(4)
	v_fma_f32 v20, -v230, v30, v20
	v_fma_f32 v21, -v234, v30, v21
	v_fma_f32 v24, -v142, v30, v24
	v_fma_f32 v25, -v150, v30, v25
	v_fma_f32 v20, -v231, v31, v20
	v_fma_f32 v21, -v235, v31, v21
	v_fma_f32 v24, -v143, v31, v24
	v_fma_f32 v25, -v151, v31, v25
	v_fma_f32 v20, -v232, v36, v20
	v_fma_f32 v21, -v236, v36, v21
	v_fma_f32 v24, -v144, v36, v24
	v_fma_f32 v25, -v152, v36, v25
	v_fma_f32 v20, -v233, v37, v20
	ds_read_b128 v[230:233], v109 offset:7248
	v_fma_f32 v21, -v237, v37, v21
	ds_read_b128 v[234:237], v109 offset:7504
	v_fma_f32 v24, -v145, v37, v24
	ds_read_b128 v[142:145], v109 offset:7760
	v_fma_f32 v25, -v153, v37, v25
	ds_read_b128 v[150:153], v109 offset:8016
	s_waitcnt lgkmcnt(4)
	v_fma_f32 v20, -v220, v40, v20
	v_fma_f32 v21, -v158, v40, v21
	v_fma_f32 v24, -v154, v40, v24
	v_fma_f32 v25, -v146, v40, v25
	v_fma_f32 v20, -v221, v41, v20
	v_fma_f32 v21, -v159, v41, v21
	v_fma_f32 v24, -v155, v41, v24
	v_fma_f32 v25, -v147, v41, v25
	v_fma_f32 v20, -v222, v44, v20
	v_fma_f32 v21, -v160, v44, v21
	v_fma_f32 v24, -v156, v44, v24
	v_fma_f32 v25, -v148, v44, v25
	v_fma_f32 v20, -v223, v45, v20
	ds_read_b128 v[220:223], v109 offset:7264
	v_fma_f32 v21, -v161, v45, v21
	ds_read_b128 v[158:161], v109 offset:7520
	v_fma_f32 v24, -v157, v45, v24
	ds_read_b128 v[154:157], v109 offset:7776
	v_fma_f32 v25, -v149, v45, v25
	ds_read_b128 v[146:149], v109 offset:8032
	s_waitcnt lgkmcnt(4)
	v_fma_f32 v20, -v230, v50, v20
	v_fma_f32 v21, -v234, v50, v21
	v_fma_f32 v24, -v142, v50, v24
	v_fma_f32 v25, -v150, v50, v25
	v_fma_f32 v20, -v231, v51, v20
	v_fma_f32 v21, -v235, v51, v21
	v_fma_f32 v24, -v143, v51, v24
	v_fma_f32 v25, -v151, v51, v25
	v_fma_f32 v20, -v232, v54, v20
	v_fma_f32 v21, -v236, v54, v21
	v_fma_f32 v24, -v144, v54, v24
	v_fma_f32 v25, -v152, v54, v25
	v_fma_f32 v20, -v233, v55, v20
	ds_read_b128 v[230:233], v109 offset:7536
	v_fma_f32 v21, -v237, v55, v21
	ds_read_b128 v[234:237], v109 offset:8192
	v_fma_f32 v24, -v145, v55, v24
	ds_read_b128 v[142:145], v109 offset:8448
	v_fma_f32 v25, -v153, v55, v25
	ds_read_b128 v[150:153], v109 offset:8704
	s_waitcnt lgkmcnt(4)
; #define LAS __attribute__((address_space(3)))
; __device__ __forceinline__ void gdn_local_unit(LAS unsigned char* lds, const GdnP& P, int unit, const int tid, const int pf) {
;     ...
;         for (int c = 1; c < 64; ++c) { f32x2 sp = (f32x2){sol2[c >> 1][c & 1], 0.f};
; #pragma unroll
;             for (int jb = 0; jb <= (c - 1) / 4; ++jb) { const f32x4 m4 = *(const LAS f32x4*)(Ms + c * 64 + 4 * jb);
;                 sp -= (f32x2){m4.x, m4.y} * sol2[2 * jb]; sp -= (f32x2){m4.z, m4.w} * sol2[2 * jb + 1]; }
;             sol2[c >> 1][c & 1] = sp.x + sp.y; }
	v_fma_f32 v20, -v220, v60, v20
	v_fma_f32 v21, -v158, v60, v21
	v_fma_f32 v24, -v154, v60, v24
	v_fma_f32 v25, -v146, v60, v25
	v_fma_f32 v20, -v221, v61, v20
	v_fma_f32 v21, -v159, v61, v21
	v_fma_f32 v24, -v155, v61, v24
	v_fma_f32 v25, -v147, v61, v25
	v_fma_f32 v20, -v222, v64, v20
	v_fma_f32 v21, -v160, v64, v21
	v_fma_f32 v24, -v156, v64, v24
	v_fma_f32 v25, -v148, v64, v25
	v_fma_f32 v70, -v223, v65, v20
	ds_read_b128 v[220:223], v109 offset:7792
	v_fma_f32 v21, -v161, v65, v21
	ds_read_b128 v[158:161], v109 offset:8960
	v_fma_f32 v24, -v157, v65, v24
	ds_read_b128 v[154:157], v109 offset:8048
	v_fma_f32 v25, -v149, v65, v25
	ds_read_b128 v[146:149], v109 offset:8208
	s_waitcnt lgkmcnt(4)
	v_fma_f32 v71, -v230, v70, v21
	ds_read_b128 v[230:233], v109 offset:8464
	v_fma_f32 v10, -v234, v0, v116
	v_fma_f32 v11, -v142, v0, v117
	v_fma_f32 v16, -v150, v0, v122
	s_waitcnt lgkmcnt(3)
	v_fma_f32 v24, -v220, v70, v24
	v_fma_f32 v17, -v158, v0, v123
	v_fma_f32 v10, -v235, v1, v10
	v_fma_f32 v11, -v143, v1, v11
	s_waitcnt lgkmcnt(2)
	v_fma_f32 v25, -v154, v70, v25
	v_fma_f32 v16, -v151, v1, v16
	v_fma_f32 v17, -v159, v1, v17
	v_fma_f32 v10, -v236, v8, v10
	v_fma_f32 v112, -v221, v71, v24
	ds_read_b128 v[220:223], v109 offset:8720
	v_fma_f32 v11, -v144, v8, v11
	v_fma_f32 v16, -v152, v8, v16
	v_fma_f32 v17, -v160, v8, v17
	v_fma_f32 v25, -v155, v71, v25
	v_fma_f32 v10, -v237, v9, v10
	ds_read_b128 v[234:237], v109 offset:8976
	v_fma_f32 v11, -v145, v9, v11
	ds_read_b128 v[142:145], v109 offset:8224
	v_fma_f32 v16, -v153, v9, v16
	ds_read_b128 v[150:153], v109 offset:8480
	v_fma_f32 v113, -v156, v112, v25
	ds_read_b128 v[154:157], v109 offset:8736
	v_fma_f32 v17, -v161, v9, v17
	ds_read_b128 v[158:161], v109 offset:8992
	s_waitcnt lgkmcnt(4)
	v_fma_f32 v10, -v146, v14, v10
	v_fma_f32 v11, -v230, v14, v11
	v_fma_f32 v16, -v220, v14, v16
	v_fma_f32 v17, -v234, v14, v17
	v_fma_f32 v10, -v147, v15, v10
	v_fma_f32 v11, -v231, v15, v11
	v_fma_f32 v16, -v221, v15, v16
	v_fma_f32 v17, -v235, v15, v17
	v_fma_f32 v10, -v148, v18, v10
	v_fma_f32 v11, -v232, v18, v11
	v_fma_f32 v16, -v222, v18, v16
	v_fma_f32 v17, -v236, v18, v17
	v_fma_f32 v10, -v149, v19, v10
	ds_read_b128 v[146:149], v109 offset:8240
	v_fma_f32 v11, -v233, v19, v11
	ds_read_b128 v[230:233], v109 offset:8496
	v_fma_f32 v16, -v223, v19, v16
	ds_read_b128 v[220:223], v109 offset:8752
	v_fma_f32 v17, -v237, v19, v17
	ds_read_b128 v[234:237], v109 offset:9008
	s_waitcnt lgkmcnt(4)
	v_fma_f32 v10, -v142, v22, v10
	v_fma_f32 v11, -v150, v22, v11
	v_fma_f32 v16, -v154, v22, v16
	v_fma_f32 v17, -v158, v22, v17
	v_fma_f32 v10, -v143, v23, v10
	v_fma_f32 v11, -v151, v23, v11
	v_fma_f32 v16, -v155, v23, v16
	v_fma_f32 v17, -v159, v23, v17
	v_fma_f32 v10, -v144, v26, v10
	v_fma_f32 v11, -v152, v26, v11
	v_fma_f32 v16, -v156, v26, v16
	v_fma_f32 v17, -v160, v26, v17
	v_fma_f32 v10, -v145, v27, v10
	ds_read_b128 v[142:145], v109 offset:8256
	v_fma_f32 v11, -v153, v27, v11
	ds_read_b128 v[150:153], v109 offset:8512
	v_fma_f32 v16, -v157, v27, v16
	ds_read_b128 v[154:157], v109 offset:8768
	v_fma_f32 v17, -v161, v27, v17
	ds_read_b128 v[158:161], v109 offset:9024
	s_waitcnt lgkmcnt(4)
	v_fma_f32 v10, -v146, v30, v10
	v_fma_f32 v11, -v230, v30, v11
	v_fma_f32 v16, -v220, v30, v16
	v_fma_f32 v17, -v234, v30, v17
	v_fma_f32 v10, -v147, v31, v10
	v_fma_f32 v11, -v231, v31, v11
	v_fma_f32 v16, -v221, v31, v16
	v_fma_f32 v17, -v235, v31, v17
	v_fma_f32 v10, -v148, v36, v10
	v_fma_f32 v11, -v232, v36, v11
	v_fma_f32 v16, -v222, v36, v16
	v_fma_f32 v17, -v236, v36, v17
	v_fma_f32 v10, -v149, v37, v10
	ds_read_b128 v[146:149], v109 offset:8272
	v_fma_f32 v11, -v233, v37, v11
	ds_read_b128 v[230:233], v109 offset:8528
	v_fma_f32 v16, -v223, v37, v16
	ds_read_b128 v[220:223], v109 offset:8784
	v_fma_f32 v17, -v237, v37, v17
	ds_read_b128 v[234:237], v109 offset:9040
	s_waitcnt lgkmcnt(4)
	v_fma_f32 v10, -v142, v40, v10
	v_fma_f32 v11, -v150, v40, v11
	v_fma_f32 v16, -v154, v40, v16
	v_fma_f32 v17, -v158, v40, v17
	v_fma_f32 v10, -v143, v41, v10
	v_fma_f32 v11, -v151, v41, v11
	v_fma_f32 v16, -v155, v41, v16
	v_fma_f32 v17, -v159, v41, v17
	v_fma_f32 v10, -v144, v44, v10
	v_fma_f32 v11, -v152, v44, v11
	v_fma_f32 v16, -v156, v44, v16
	v_fma_f32 v17, -v160, v44, v17
	v_fma_f32 v10, -v145, v45, v10
	ds_read_b128 v[142:145], v109 offset:8288
	v_fma_f32 v11, -v153, v45, v11
	ds_read_b128 v[150:153], v109 offset:8544
	v_fma_f32 v16, -v157, v45, v16
	ds_read_b128 v[154:157], v109 offset:8800
	v_fma_f32 v17, -v161, v45, v17
	ds_read_b128 v[158:161], v109 offset:9056
	s_waitcnt lgkmcnt(4)
	v_fma_f32 v10, -v146, v50, v10
	v_fma_f32 v11, -v230, v50, v11
	v_fma_f32 v16, -v220, v50, v16
	v_fma_f32 v17, -v234, v50, v17
	v_fma_f32 v10, -v147, v51, v10
	v_fma_f32 v11, -v231, v51, v11
	v_fma_f32 v16, -v221, v51, v16
	v_fma_f32 v17, -v235, v51, v17
	v_fma_f32 v10, -v148, v54, v10
	v_fma_f32 v11, -v232, v54, v11
	v_fma_f32 v16, -v222, v54, v16
	v_fma_f32 v17, -v236, v54, v17
	v_fma_f32 v10, -v149, v55, v10
	ds_read_b128 v[146:149], v109 offset:8304
	v_fma_f32 v11, -v233, v55, v11
	ds_read_b128 v[230:233], v109 offset:8560
	v_fma_f32 v16, -v223, v55, v16
	ds_read_b128 v[220:223], v109 offset:8816
	v_fma_f32 v17, -v237, v55, v17
	ds_read_b128 v[234:237], v109 offset:9072
	s_waitcnt lgkmcnt(4)
; #define LAS __attribute__((address_space(3)))
; __device__ __forceinline__ void gdn_local_unit(LAS unsigned char* lds, const GdnP& P, int unit, const int tid, const int pf) {
;     ...
;         for (int c = 1; c < 64; ++c) { f32x2 sp = (f32x2){sol2[c >> 1][c & 1], 0.f};
; #pragma unroll
;             for (int jb = 0; jb <= (c - 1) / 4; ++jb) { const f32x4 m4 = *(const LAS f32x4*)(Ms + c * 64 + 4 * jb);
;                 sp -= (f32x2){m4.x, m4.y} * sol2[2 * jb]; sp -= (f32x2){m4.z, m4.w} * sol2[2 * jb + 1]; }
;             sol2[c >> 1][c & 1] = sp.x + sp.y; }
	v_fma_f32 v10, -v142, v60, v10
	v_fma_f32 v11, -v150, v60, v11
	v_fma_f32 v16, -v154, v60, v16
	v_fma_f32 v17, -v158, v60, v17
	v_fma_f32 v10, -v143, v61, v10
	v_fma_f32 v11, -v151, v61, v11
	v_fma_f32 v16, -v155, v61, v16
	v_fma_f32 v17, -v159, v61, v17
	v_fma_f32 v10, -v144, v64, v10
	v_fma_f32 v11, -v152, v64, v11
	v_fma_f32 v16, -v156, v64, v16
	v_fma_f32 v17, -v160, v64, v17
	v_fma_f32 v10, -v145, v65, v10
	ds_read_b128 v[142:145], v109 offset:8576
	v_fma_f32 v11, -v153, v65, v11
	ds_read_b128 v[150:153], v109 offset:9216
	v_fma_f32 v16, -v157, v65, v16
	ds_read_b128 v[154:157], v109 offset:9472
	v_fma_f32 v17, -v161, v65, v17
	ds_read_b128 v[158:161], v109 offset:9728
	s_waitcnt lgkmcnt(4)
	v_fma_f32 v10, -v146, v70, v10
	v_fma_f32 v11, -v230, v70, v11
	v_fma_f32 v16, -v220, v70, v16
	v_fma_f32 v17, -v234, v70, v17
	v_fma_f32 v10, -v147, v71, v10
	v_fma_f32 v11, -v231, v71, v11
	v_fma_f32 v16, -v221, v71, v16
	v_fma_f32 v17, -v235, v71, v17
	v_fma_f32 v10, -v148, v112, v10
	v_fma_f32 v11, -v232, v112, v11
	v_fma_f32 v16, -v222, v112, v16
	v_fma_f32 v17, -v236, v112, v17
	v_fma_f32 v116, -v149, v113, v10
	ds_read_b128 v[146:149], v109 offset:8832
	v_fma_f32 v11, -v233, v113, v11
	ds_read_b128 v[230:233], v109 offset:9984
	v_fma_f32 v16, -v223, v113, v16
	ds_read_b128 v[220:223], v109 offset:9088
	v_fma_f32 v17, -v237, v113, v17
	ds_read_b128 v[234:237], v109 offset:9232
	s_waitcnt lgkmcnt(4)
	v_fma_f32 v117, -v142, v116, v11
	ds_read_b128 v[142:145], v109 offset:9488
	v_fma_f32 v20, -v150, v0, v128
	v_fma_f32 v21, -v154, v0, v129
	v_fma_f32 v24, -v158, v0, v134
	s_waitcnt lgkmcnt(3)
	v_fma_f32 v16, -v146, v116, v16
	v_fma_f32 v25, -v230, v0, v135
	v_fma_f32 v20, -v151, v1, v20
	v_fma_f32 v21, -v155, v1, v21
	s_waitcnt lgkmcnt(2)
	v_fma_f32 v17, -v220, v116, v17
	v_fma_f32 v24, -v159, v1, v24
	v_fma_f32 v25, -v231, v1, v25
	v_fma_f32 v20, -v152, v8, v20
	v_fma_f32 v122, -v147, v117, v16
	ds_read_b128 v[146:149], v109 offset:9744
	v_fma_f32 v21, -v156, v8, v21
	v_fma_f32 v24, -v160, v8, v24
	v_fma_f32 v25, -v232, v8, v25
	v_fma_f32 v17, -v221, v117, v17
	v_fma_f32 v20, -v153, v9, v20
	ds_read_b128 v[150:153], v109 offset:10000
	v_fma_f32 v21, -v157, v9, v21
	ds_read_b128 v[154:157], v109 offset:9248
	v_fma_f32 v24, -v161, v9, v24
	ds_read_b128 v[158:161], v109 offset:9504
	v_fma_f32 v123, -v222, v122, v17
	ds_read_b128 v[220:223], v109 offset:9760
	v_fma_f32 v25, -v233, v9, v25
	ds_read_b128 v[230:233], v109 offset:10016
	s_waitcnt lgkmcnt(4)
	v_fma_f32 v20, -v234, v14, v20
	v_fma_f32 v21, -v142, v14, v21
	v_fma_f32 v24, -v146, v14, v24
	v_fma_f32 v25, -v150, v14, v25
	v_fma_f32 v20, -v235, v15, v20
	v_fma_f32 v21, -v143, v15, v21
	v_fma_f32 v24, -v147, v15, v24
	v_fma_f32 v25, -v151, v15, v25
	v_fma_f32 v20, -v236, v18, v20
	v_fma_f32 v21, -v144, v18, v21
	v_fma_f32 v24, -v148, v18, v24
	v_fma_f32 v25, -v152, v18, v25
	v_fma_f32 v20, -v237, v19, v20
	ds_read_b128 v[234:237], v109 offset:9264
	v_fma_f32 v21, -v145, v19, v21
	ds_read_b128 v[142:145], v109 offset:9520
	v_fma_f32 v24, -v149, v19, v24
	ds_read_b128 v[146:149], v109 offset:9776
	v_fma_f32 v25, -v153, v19, v25
	ds_read_b128 v[150:153], v109 offset:10032
	s_waitcnt lgkmcnt(4)
	v_fma_f32 v20, -v154, v22, v20
	v_fma_f32 v21, -v158, v22, v21
	v_fma_f32 v24, -v220, v22, v24
	v_fma_f32 v25, -v230, v22, v25
	v_fma_f32 v20, -v155, v23, v20
	v_fma_f32 v21, -v159, v23, v21
	v_fma_f32 v24, -v221, v23, v24
	v_fma_f32 v25, -v231, v23, v25
	v_fma_f32 v20, -v156, v26, v20
	v_fma_f32 v21, -v160, v26, v21
	v_fma_f32 v24, -v222, v26, v24
	v_fma_f32 v25, -v232, v26, v25
	v_fma_f32 v20, -v157, v27, v20
	ds_read_b128 v[154:157], v109 offset:9280
	v_fma_f32 v21, -v161, v27, v21
	ds_read_b128 v[158:161], v109 offset:9536
	v_fma_f32 v24, -v223, v27, v24
	ds_read_b128 v[220:223], v109 offset:9792
	v_fma_f32 v25, -v233, v27, v25
	ds_read_b128 v[230:233], v109 offset:10048
	s_waitcnt lgkmcnt(4)
	v_fma_f32 v20, -v234, v30, v20
	v_fma_f32 v21, -v142, v30, v21
	v_fma_f32 v24, -v146, v30, v24
	v_fma_f32 v25, -v150, v30, v25
	v_fma_f32 v20, -v235, v31, v20
	v_fma_f32 v21, -v143, v31, v21
	v_fma_f32 v24, -v147, v31, v24
	v_fma_f32 v25, -v151, v31, v25
	v_fma_f32 v20, -v236, v36, v20
	v_fma_f32 v21, -v144, v36, v21
	v_fma_f32 v24, -v148, v36, v24
	v_fma_f32 v25, -v152, v36, v25
	v_fma_f32 v20, -v237, v37, v20
	ds_read_b128 v[234:237], v109 offset:9296
	v_fma_f32 v21, -v145, v37, v21
	ds_read_b128 v[142:145], v109 offset:9552
	v_fma_f32 v24, -v149, v37, v24
	ds_read_b128 v[146:149], v109 offset:9808
	v_fma_f32 v25, -v153, v37, v25
	ds_read_b128 v[150:153], v109 offset:10064
	s_waitcnt lgkmcnt(4)
	v_fma_f32 v20, -v154, v40, v20
	v_fma_f32 v21, -v158, v40, v21
	v_fma_f32 v24, -v220, v40, v24
	v_fma_f32 v25, -v230, v40, v25
	v_fma_f32 v20, -v155, v41, v20
	v_fma_f32 v21, -v159, v41, v21
	v_fma_f32 v24, -v221, v41, v24
	v_fma_f32 v25, -v231, v41, v25
	v_fma_f32 v20, -v156, v44, v20
	v_fma_f32 v21, -v160, v44, v21
	v_fma_f32 v24, -v222, v44, v24
	v_fma_f32 v25, -v232, v44, v25
	v_fma_f32 v20, -v157, v45, v20
	ds_read_b128 v[154:157], v109 offset:9312
	v_fma_f32 v21, -v161, v45, v21
	ds_read_b128 v[158:161], v109 offset:9568
	v_fma_f32 v24, -v223, v45, v24
	ds_read_b128 v[220:223], v109 offset:9824
	v_fma_f32 v25, -v233, v45, v25
	ds_read_b128 v[230:233], v109 offset:10080
	s_waitcnt lgkmcnt(4)
; #define LAS __attribute__((address_space(3)))
; __device__ __forceinline__ void gdn_local_unit(LAS unsigned char* lds, const GdnP& P, int unit, const int tid, const int pf) {
;     ...
;         for (int c = 1; c < 64; ++c) { f32x2 sp = (f32x2){sol2[c >> 1][c & 1], 0.f};
; #pragma unroll
;             for (int jb = 0; jb <= (c - 1) / 4; ++jb) { const f32x4 m4 = *(const LAS f32x4*)(Ms + c * 64 + 4 * jb);
;                 sp -= (f32x2){m4.x, m4.y} * sol2[2 * jb]; sp -= (f32x2){m4.z, m4.w} * sol2[2 * jb + 1]; }
;             sol2[c >> 1][c & 1] = sp.x + sp.y; }
	v_fma_f32 v20, -v234, v50, v20
	v_fma_f32 v21, -v142, v50, v21
	v_fma_f32 v24, -v146, v50, v24
	v_fma_f32 v25, -v150, v50, v25
	v_fma_f32 v20, -v235, v51, v20
	v_fma_f32 v21, -v143, v51, v21
	v_fma_f32 v24, -v147, v51, v24
	v_fma_f32 v25, -v151, v51, v25
	v_fma_f32 v20, -v236, v54, v20
	v_fma_f32 v21, -v144, v54, v21
	v_fma_f32 v24, -v148, v54, v24
	v_fma_f32 v25, -v152, v54, v25
	v_fma_f32 v20, -v237, v55, v20
	ds_read_b128 v[234:237], v109 offset:9328
	v_fma_f32 v21, -v145, v55, v21
	ds_read_b128 v[142:145], v109 offset:9584
	v_fma_f32 v24, -v149, v55, v24
	ds_read_b128 v[146:149], v109 offset:9840
	v_fma_f32 v25, -v153, v55, v25
	ds_read_b128 v[150:153], v109 offset:10096
	s_waitcnt lgkmcnt(4)
	v_fma_f32 v20, -v154, v60, v20
	v_fma_f32 v21, -v158, v60, v21
	v_fma_f32 v24, -v220, v60, v24
	v_fma_f32 v25, -v230, v60, v25
	v_fma_f32 v20, -v155, v61, v20
	v_fma_f32 v21, -v159, v61, v21
	v_fma_f32 v24, -v221, v61, v24
	v_fma_f32 v25, -v231, v61, v25
	v_fma_f32 v20, -v156, v64, v20
	v_fma_f32 v21, -v160, v64, v21
	v_fma_f32 v24, -v222, v64, v24
	v_fma_f32 v25, -v232, v64, v25
	v_fma_f32 v20, -v157, v65, v20
	ds_read_b128 v[154:157], v109 offset:9344
	v_fma_f32 v21, -v161, v65, v21
	ds_read_b128 v[158:161], v109 offset:9600
	v_fma_f32 v24, -v223, v65, v24
	ds_read_b128 v[220:223], v109 offset:9856
	v_fma_f32 v25, -v233, v65, v25
	ds_read_b128 v[230:233], v109 offset:10112
	s_waitcnt lgkmcnt(4)
	v_fma_f32 v20, -v234, v70, v20
	v_fma_f32 v21, -v142, v70, v21
	v_fma_f32 v24, -v146, v70, v24
	v_fma_f32 v25, -v150, v70, v25
	v_fma_f32 v20, -v235, v71, v20
	v_fma_f32 v21, -v143, v71, v21
	v_fma_f32 v24, -v147, v71, v24
	v_fma_f32 v25, -v151, v71, v25
	v_fma_f32 v20, -v236, v112, v20
	v_fma_f32 v21, -v144, v112, v21
	v_fma_f32 v24, -v148, v112, v24
	v_fma_f32 v25, -v152, v112, v25
	v_fma_f32 v20, -v237, v113, v20
	ds_read_b128 v[234:237], v109 offset:9616
	v_fma_f32 v21, -v145, v113, v21
	ds_read_b128 v[142:145], v109 offset:10240
	v_fma_f32 v24, -v149, v113, v24
	ds_read_b128 v[146:149], v109 offset:10496
	v_fma_f32 v25, -v153, v113, v25
	ds_read_b128 v[150:153], v109 offset:10752
	s_waitcnt lgkmcnt(4)
	v_fma_f32 v20, -v154, v116, v20
	v_fma_f32 v21, -v158, v116, v21
	v_fma_f32 v24, -v220, v116, v24
	v_fma_f32 v25, -v230, v116, v25
	v_fma_f32 v20, -v155, v117, v20
	v_fma_f32 v21, -v159, v117, v21
	v_fma_f32 v24, -v221, v117, v24
	v_fma_f32 v25, -v231, v117, v25
	v_fma_f32 v20, -v156, v122, v20
	v_fma_f32 v21, -v160, v122, v21
	v_fma_f32 v24, -v222, v122, v24
	v_fma_f32 v25, -v232, v122, v25
	v_fma_f32 v128, -v157, v123, v20
	ds_read_b128 v[154:157], v109 offset:9872
	v_fma_f32 v21, -v161, v123, v21
	ds_read_b128 v[158:161], v109 offset:11008
	v_fma_f32 v24, -v223, v123, v24
	ds_read_b128 v[220:223], v109 offset:10128
	v_fma_f32 v25, -v233, v123, v25
	ds_read_b128 v[230:233], v109 offset:10256
	s_waitcnt lgkmcnt(4)
	v_fma_f32 v129, -v234, v128, v21
	ds_read_b128 v[234:237], v109 offset:10512
	v_fma_f32 v10, -v142, v0, v140
	v_fma_f32 v11, -v146, v0, v141
	v_fma_f32 v16, -v150, v0, v138
	s_waitcnt lgkmcnt(3)
	v_fma_f32 v24, -v154, v128, v24
	v_fma_f32 v17, -v158, v0, v139
	v_fma_f32 v10, -v143, v1, v10
	v_fma_f32 v11, -v147, v1, v11
	s_waitcnt lgkmcnt(2)
	v_fma_f32 v25, -v220, v128, v25
	v_fma_f32 v16, -v151, v1, v16
	v_fma_f32 v17, -v159, v1, v17
	v_fma_f32 v10, -v144, v8, v10
	v_fma_f32 v134, -v155, v129, v24
	ds_read_b128 v[154:157], v109 offset:10768
	v_fma_f32 v11, -v148, v8, v11
	v_fma_f32 v16, -v152, v8, v16
	v_fma_f32 v17, -v160, v8, v17
	v_fma_f32 v25, -v221, v129, v25
	v_fma_f32 v10, -v145, v9, v10
	ds_read_b128 v[142:145], v109 offset:11024
	v_fma_f32 v11, -v149, v9, v11
	ds_read_b128 v[146:149], v109 offset:10272
	v_fma_f32 v16, -v153, v9, v16
	ds_read_b128 v[150:153], v109 offset:10528
	v_fma_f32 v135, -v222, v134, v25
	ds_read_b128 v[220:223], v109 offset:10784
	v_fma_f32 v17, -v161, v9, v17
	ds_read_b128 v[158:161], v109 offset:11040
	s_waitcnt lgkmcnt(4)
	v_fma_f32 v10, -v230, v14, v10
	v_fma_f32 v11, -v234, v14, v11
	v_fma_f32 v16, -v154, v14, v16
	v_fma_f32 v17, -v142, v14, v17
	v_fma_f32 v10, -v231, v15, v10
	v_fma_f32 v11, -v235, v15, v11
	v_fma_f32 v16, -v155, v15, v16
	v_fma_f32 v17, -v143, v15, v17
	v_fma_f32 v10, -v232, v18, v10
	v_fma_f32 v11, -v236, v18, v11
	v_fma_f32 v16, -v156, v18, v16
	v_fma_f32 v17, -v144, v18, v17
	v_fma_f32 v10, -v233, v19, v10
	ds_read_b128 v[230:233], v109 offset:10288
	v_fma_f32 v11, -v237, v19, v11
	ds_read_b128 v[234:237], v109 offset:10544
	v_fma_f32 v16, -v157, v19, v16
	ds_read_b128 v[154:157], v109 offset:10800
	v_fma_f32 v17, -v145, v19, v17
	ds_read_b128 v[142:145], v109 offset:11056
	s_waitcnt lgkmcnt(4)
	v_fma_f32 v10, -v146, v22, v10
	v_fma_f32 v11, -v150, v22, v11
	v_fma_f32 v16, -v220, v22, v16
	v_fma_f32 v17, -v158, v22, v17
	v_fma_f32 v10, -v147, v23, v10
	v_fma_f32 v11, -v151, v23, v11
	v_fma_f32 v16, -v221, v23, v16
	v_fma_f32 v17, -v159, v23, v17
	v_fma_f32 v10, -v148, v26, v10
	v_fma_f32 v11, -v152, v26, v11
	v_fma_f32 v16, -v222, v26, v16
	v_fma_f32 v17, -v160, v26, v17
	v_fma_f32 v10, -v149, v27, v10
	ds_read_b128 v[146:149], v109 offset:10304
	v_fma_f32 v11, -v153, v27, v11
	ds_read_b128 v[150:153], v109 offset:10560
	v_fma_f32 v16, -v223, v27, v16
	ds_read_b128 v[220:223], v109 offset:10816
	v_fma_f32 v17, -v161, v27, v17
	ds_read_b128 v[158:161], v109 offset:11072
	s_waitcnt lgkmcnt(4)
; #define LAS __attribute__((address_space(3)))
; __device__ __forceinline__ void gdn_local_unit(LAS unsigned char* lds, const GdnP& P, int unit, const int tid, const int pf) {
;     ...
;         for (int c = 1; c < 64; ++c) { f32x2 sp = (f32x2){sol2[c >> 1][c & 1], 0.f};
; #pragma unroll
;             for (int jb = 0; jb <= (c - 1) / 4; ++jb) { const f32x4 m4 = *(const LAS f32x4*)(Ms + c * 64 + 4 * jb);
;                 sp -= (f32x2){m4.x, m4.y} * sol2[2 * jb]; sp -= (f32x2){m4.z, m4.w} * sol2[2 * jb + 1]; }
;             sol2[c >> 1][c & 1] = sp.x + sp.y; }
	v_fma_f32 v10, -v230, v30, v10
	v_fma_f32 v11, -v234, v30, v11
	v_fma_f32 v16, -v154, v30, v16
	v_fma_f32 v17, -v142, v30, v17
	v_fma_f32 v10, -v231, v31, v10
	v_fma_f32 v11, -v235, v31, v11
	v_fma_f32 v16, -v155, v31, v16
	v_fma_f32 v17, -v143, v31, v17
	v_fma_f32 v10, -v232, v36, v10
	v_fma_f32 v11, -v236, v36, v11
	v_fma_f32 v16, -v156, v36, v16
	v_fma_f32 v17, -v144, v36, v17
	v_fma_f32 v10, -v233, v37, v10
	ds_read_b128 v[230:233], v109 offset:10320
	v_fma_f32 v11, -v237, v37, v11
	ds_read_b128 v[234:237], v109 offset:10576
	v_fma_f32 v16, -v157, v37, v16
	ds_read_b128 v[154:157], v109 offset:10832
	v_fma_f32 v17, -v145, v37, v17
	ds_read_b128 v[142:145], v109 offset:11088
	s_waitcnt lgkmcnt(4)
	v_fma_f32 v10, -v146, v40, v10
	v_fma_f32 v11, -v150, v40, v11
	v_fma_f32 v16, -v220, v40, v16
	v_fma_f32 v17, -v158, v40, v17
	v_fma_f32 v10, -v147, v41, v10
	v_fma_f32 v11, -v151, v41, v11
	v_fma_f32 v16, -v221, v41, v16
	v_fma_f32 v17, -v159, v41, v17
	v_fma_f32 v10, -v148, v44, v10
	v_fma_f32 v11, -v152, v44, v11
	v_fma_f32 v16, -v222, v44, v16
	v_fma_f32 v17, -v160, v44, v17
	v_fma_f32 v10, -v149, v45, v10
	ds_read_b128 v[146:149], v109 offset:10336
	v_fma_f32 v11, -v153, v45, v11
	ds_read_b128 v[150:153], v109 offset:10592
	v_fma_f32 v16, -v223, v45, v16
	ds_read_b128 v[220:223], v109 offset:10848
	v_fma_f32 v17, -v161, v45, v17
	ds_read_b128 v[158:161], v109 offset:11104
	s_waitcnt lgkmcnt(4)
	v_fma_f32 v10, -v230, v50, v10
	v_fma_f32 v11, -v234, v50, v11
	v_fma_f32 v16, -v154, v50, v16
	v_fma_f32 v17, -v142, v50, v17
	v_fma_f32 v10, -v231, v51, v10
	v_fma_f32 v11, -v235, v51, v11
	v_fma_f32 v16, -v155, v51, v16
	v_fma_f32 v17, -v143, v51, v17
	v_fma_f32 v10, -v232, v54, v10
	v_fma_f32 v11, -v236, v54, v11
	v_fma_f32 v16, -v156, v54, v16
	v_fma_f32 v17, -v144, v54, v17
	v_fma_f32 v10, -v233, v55, v10
	ds_read_b128 v[230:233], v109 offset:10352
	v_fma_f32 v11, -v237, v55, v11
	ds_read_b128 v[234:237], v109 offset:10608
	v_fma_f32 v16, -v157, v55, v16
	ds_read_b128 v[154:157], v109 offset:10864
	v_fma_f32 v17, -v145, v55, v17
	ds_read_b128 v[142:145], v109 offset:11120
	s_waitcnt lgkmcnt(4)
	v_fma_f32 v10, -v146, v60, v10
	v_fma_f32 v11, -v150, v60, v11
	v_fma_f32 v16, -v220, v60, v16
	v_fma_f32 v17, -v158, v60, v17
	v_fma_f32 v10, -v147, v61, v10
	v_fma_f32 v11, -v151, v61, v11
	v_fma_f32 v16, -v221, v61, v16
	v_fma_f32 v17, -v159, v61, v17
	v_fma_f32 v10, -v148, v64, v10
	v_fma_f32 v11, -v152, v64, v11
	v_fma_f32 v16, -v222, v64, v16
	v_fma_f32 v17, -v160, v64, v17
	v_fma_f32 v10, -v149, v65, v10
	ds_read_b128 v[146:149], v109 offset:10368
	v_fma_f32 v11, -v153, v65, v11
	ds_read_b128 v[150:153], v109 offset:10624
	v_fma_f32 v16, -v223, v65, v16
	ds_read_b128 v[220:223], v109 offset:10880
	v_fma_f32 v17, -v161, v65, v17
	ds_read_b128 v[158:161], v109 offset:11136
	s_waitcnt lgkmcnt(4)
	v_fma_f32 v10, -v230, v70, v10
	v_fma_f32 v11, -v234, v70, v11
	v_fma_f32 v16, -v154, v70, v16
	v_fma_f32 v17, -v142, v70, v17
	v_fma_f32 v10, -v231, v71, v10
	v_fma_f32 v11, -v235, v71, v11
	v_fma_f32 v16, -v155, v71, v16
	v_fma_f32 v17, -v143, v71, v17
	v_fma_f32 v10, -v232, v112, v10
	v_fma_f32 v11, -v236, v112, v11
	v_fma_f32 v16, -v156, v112, v16
	v_fma_f32 v17, -v144, v112, v17
	v_fma_f32 v10, -v233, v113, v10
	ds_read_b128 v[230:233], v109 offset:10384
	v_fma_f32 v11, -v237, v113, v11
	ds_read_b128 v[234:237], v109 offset:10640
	v_fma_f32 v16, -v157, v113, v16
	ds_read_b128 v[154:157], v109 offset:10896
	v_fma_f32 v17, -v145, v113, v17
	ds_read_b128 v[142:145], v109 offset:11152
	s_waitcnt lgkmcnt(4)
	v_fma_f32 v10, -v146, v116, v10
	v_fma_f32 v11, -v150, v116, v11
	v_fma_f32 v16, -v220, v116, v16
	v_fma_f32 v17, -v158, v116, v17
	v_fma_f32 v10, -v147, v117, v10
	v_fma_f32 v11, -v151, v117, v11
	v_fma_f32 v16, -v221, v117, v16
	v_fma_f32 v17, -v159, v117, v17
	v_fma_f32 v10, -v148, v122, v10
	v_fma_f32 v11, -v152, v122, v11
	v_fma_f32 v16, -v222, v122, v16
	v_fma_f32 v17, -v160, v122, v17
	v_fma_f32 v10, -v149, v123, v10
	ds_read_b128 v[146:149], v109 offset:10656
	v_fma_f32 v11, -v153, v123, v11
	ds_read_b128 v[150:153], v109 offset:11264
	v_fma_f32 v16, -v223, v123, v16
	ds_read_b128 v[220:223], v109 offset:11520
	v_fma_f32 v17, -v161, v123, v17
	ds_read_b128 v[158:161], v109 offset:11776
	s_waitcnt lgkmcnt(4)
	v_fma_f32 v10, -v230, v128, v10
	v_fma_f32 v11, -v234, v128, v11
	v_fma_f32 v16, -v154, v128, v16
	v_fma_f32 v17, -v142, v128, v17
	v_fma_f32 v10, -v231, v129, v10
	v_fma_f32 v11, -v235, v129, v11
	v_fma_f32 v16, -v155, v129, v16
	v_fma_f32 v17, -v143, v129, v17
	v_fma_f32 v10, -v232, v134, v10
	v_fma_f32 v11, -v236, v134, v11
	v_fma_f32 v16, -v156, v134, v16
	v_fma_f32 v17, -v144, v134, v17
	v_fma_f32 v140, -v233, v135, v10
	ds_read_b128 v[230:233], v109 offset:10912
	v_fma_f32 v11, -v237, v135, v11
	ds_read_b128 v[234:237], v109 offset:12032
	v_fma_f32 v16, -v157, v135, v16
	ds_read_b128 v[154:157], v109 offset:11168
	v_fma_f32 v17, -v145, v135, v17
	ds_read_b128 v[142:145], v109 offset:11280
	s_waitcnt lgkmcnt(4)
	v_fma_f32 v141, -v146, v140, v11
	ds_read_b128 v[146:149], v109 offset:11536
	v_fma_f32 v20, -v150, v0, v132
	v_fma_f32 v21, -v220, v0, v133
	v_fma_f32 v24, -v158, v0, v124
	s_waitcnt lgkmcnt(3)
	v_fma_f32 v16, -v230, v140, v16
	v_fma_f32 v25, -v234, v0, v125
	v_fma_f32 v20, -v151, v1, v20
	v_fma_f32 v21, -v221, v1, v21
	s_waitcnt lgkmcnt(2)
; #define LAS __attribute__((address_space(3)))
; __device__ __forceinline__ void gdn_local_unit(LAS unsigned char* lds, const GdnP& P, int unit, const int tid, const int pf) {
;     ...
;         for (int c = 1; c < 64; ++c) { f32x2 sp = (f32x2){sol2[c >> 1][c & 1], 0.f};
; #pragma unroll
;             for (int jb = 0; jb <= (c - 1) / 4; ++jb) { const f32x4 m4 = *(const LAS f32x4*)(Ms + c * 64 + 4 * jb);
;                 sp -= (f32x2){m4.x, m4.y} * sol2[2 * jb]; sp -= (f32x2){m4.z, m4.w} * sol2[2 * jb + 1]; }
;             sol2[c >> 1][c & 1] = sp.x + sp.y; }
	v_fma_f32 v17, -v154, v140, v17
	v_fma_f32 v24, -v159, v1, v24
	v_fma_f32 v25, -v235, v1, v25
	v_fma_f32 v20, -v152, v8, v20
	v_fma_f32 v138, -v231, v141, v16
	ds_read_b128 v[230:233], v109 offset:11792
	v_fma_f32 v21, -v222, v8, v21
	v_fma_f32 v24, -v160, v8, v24
	v_fma_f32 v25, -v236, v8, v25
	v_fma_f32 v17, -v155, v141, v17
	v_fma_f32 v20, -v153, v9, v20
	ds_read_b128 v[150:153], v109 offset:12048
	v_fma_f32 v21, -v223, v9, v21
	ds_read_b128 v[220:223], v109 offset:11296
	v_fma_f32 v24, -v161, v9, v24
	ds_read_b128 v[158:161], v109 offset:11552
	v_fma_f32 v139, -v156, v138, v17
	ds_read_b128 v[154:157], v109 offset:11808
	v_fma_f32 v25, -v237, v9, v25
	ds_read_b128 v[234:237], v109 offset:12064
	s_waitcnt lgkmcnt(4)
	v_fma_f32 v20, -v142, v14, v20
	v_fma_f32 v21, -v146, v14, v21
	v_fma_f32 v24, -v230, v14, v24
	v_fma_f32 v25, -v150, v14, v25
	v_fma_f32 v20, -v143, v15, v20
	v_fma_f32 v21, -v147, v15, v21
	v_fma_f32 v24, -v231, v15, v24
	v_fma_f32 v25, -v151, v15, v25
	v_fma_f32 v20, -v144, v18, v20
	v_fma_f32 v21, -v148, v18, v21
	v_fma_f32 v24, -v232, v18, v24
	v_fma_f32 v25, -v152, v18, v25
	v_fma_f32 v20, -v145, v19, v20
	ds_read_b128 v[142:145], v109 offset:11312
	v_fma_f32 v21, -v149, v19, v21
	ds_read_b128 v[146:149], v109 offset:11568
	v_fma_f32 v24, -v233, v19, v24
	ds_read_b128 v[230:233], v109 offset:11824
	v_fma_f32 v25, -v153, v19, v25
	ds_read_b128 v[150:153], v109 offset:12080
	s_waitcnt lgkmcnt(4)
	v_fma_f32 v20, -v220, v22, v20
	v_fma_f32 v21, -v158, v22, v21
	v_fma_f32 v24, -v154, v22, v24
	v_fma_f32 v25, -v234, v22, v25
	v_fma_f32 v20, -v221, v23, v20
	v_fma_f32 v21, -v159, v23, v21
	v_fma_f32 v24, -v155, v23, v24
	v_fma_f32 v25, -v235, v23, v25
	v_fma_f32 v20, -v222, v26, v20
	v_fma_f32 v21, -v160, v26, v21
	v_fma_f32 v24, -v156, v26, v24
	v_fma_f32 v25, -v236, v26, v25
	v_fma_f32 v20, -v223, v27, v20
	ds_read_b128 v[220:223], v109 offset:11328
	v_fma_f32 v21, -v161, v27, v21
	ds_read_b128 v[158:161], v109 offset:11584
	v_fma_f32 v24, -v157, v27, v24
	ds_read_b128 v[154:157], v109 offset:11840
	v_fma_f32 v25, -v237, v27, v25
	ds_read_b128 v[234:237], v109 offset:12096
	s_waitcnt lgkmcnt(4)
	v_fma_f32 v20, -v142, v30, v20
	v_fma_f32 v21, -v146, v30, v21
	v_fma_f32 v24, -v230, v30, v24
	v_fma_f32 v25, -v150, v30, v25
	v_fma_f32 v20, -v143, v31, v20
	v_fma_f32 v21, -v147, v31, v21
	v_fma_f32 v24, -v231, v31, v24
	v_fma_f32 v25, -v151, v31, v25
	v_fma_f32 v20, -v144, v36, v20
	v_fma_f32 v21, -v148, v36, v21
	v_fma_f32 v24, -v232, v36, v24
	v_fma_f32 v25, -v152, v36, v25
	v_fma_f32 v20, -v145, v37, v20
	ds_read_b128 v[142:145], v109 offset:11344
	v_fma_f32 v21, -v149, v37, v21
	ds_read_b128 v[146:149], v109 offset:11600
	v_fma_f32 v24, -v233, v37, v24
	ds_read_b128 v[230:233], v109 offset:11856
	v_fma_f32 v25, -v153, v37, v25
	ds_read_b128 v[150:153], v109 offset:12112
	s_waitcnt lgkmcnt(4)
	v_fma_f32 v20, -v220, v40, v20
	v_fma_f32 v21, -v158, v40, v21
	v_fma_f32 v24, -v154, v40, v24
	v_fma_f32 v25, -v234, v40, v25
	v_fma_f32 v20, -v221, v41, v20
	v_fma_f32 v21, -v159, v41, v21
	v_fma_f32 v24, -v155, v41, v24
	v_fma_f32 v25, -v235, v41, v25
	v_fma_f32 v20, -v222, v44, v20
	v_fma_f32 v21, -v160, v44, v21
	v_fma_f32 v24, -v156, v44, v24
	v_fma_f32 v25, -v236, v44, v25
	v_fma_f32 v20, -v223, v45, v20
	ds_read_b128 v[220:223], v109 offset:11360
	v_fma_f32 v21, -v161, v45, v21
	ds_read_b128 v[158:161], v109 offset:11616
	v_fma_f32 v24, -v157, v45, v24
	ds_read_b128 v[154:157], v109 offset:11872
	v_fma_f32 v25, -v237, v45, v25
	ds_read_b128 v[234:237], v109 offset:12128
	s_waitcnt lgkmcnt(4)
	v_fma_f32 v20, -v142, v50, v20
	v_fma_f32 v21, -v146, v50, v21
	v_fma_f32 v24, -v230, v50, v24
	v_fma_f32 v25, -v150, v50, v25
	v_fma_f32 v20, -v143, v51, v20
	v_fma_f32 v21, -v147, v51, v21
	v_fma_f32 v24, -v231, v51, v24
	v_fma_f32 v25, -v151, v51, v25
	v_fma_f32 v20, -v144, v54, v20
	v_fma_f32 v21, -v148, v54, v21
	v_fma_f32 v24, -v232, v54, v24
	v_fma_f32 v25, -v152, v54, v25
	v_fma_f32 v20, -v145, v55, v20
	ds_read_b128 v[142:145], v109 offset:11376
	v_fma_f32 v21, -v149, v55, v21
	ds_read_b128 v[146:149], v109 offset:11632
	v_fma_f32 v24, -v233, v55, v24
	ds_read_b128 v[230:233], v109 offset:11888
	v_fma_f32 v25, -v153, v55, v25
	ds_read_b128 v[150:153], v109 offset:12144
	s_waitcnt lgkmcnt(4)
	v_fma_f32 v20, -v220, v60, v20
	v_fma_f32 v21, -v158, v60, v21
	v_fma_f32 v24, -v154, v60, v24
	v_fma_f32 v25, -v234, v60, v25
	v_fma_f32 v20, -v221, v61, v20
	v_fma_f32 v21, -v159, v61, v21
	v_fma_f32 v24, -v155, v61, v24
	v_fma_f32 v25, -v235, v61, v25
	v_fma_f32 v20, -v222, v64, v20
	v_fma_f32 v21, -v160, v64, v21
	v_fma_f32 v24, -v156, v64, v24
	v_fma_f32 v25, -v236, v64, v25
	v_fma_f32 v20, -v223, v65, v20
	ds_read_b128 v[220:223], v109 offset:11392
	v_fma_f32 v21, -v161, v65, v21
	ds_read_b128 v[158:161], v109 offset:11648
	v_fma_f32 v24, -v157, v65, v24
	ds_read_b128 v[154:157], v109 offset:11904
	v_fma_f32 v25, -v237, v65, v25
	ds_read_b128 v[234:237], v109 offset:12160
	s_waitcnt lgkmcnt(4)
	v_fma_f32 v20, -v142, v70, v20
	v_fma_f32 v21, -v146, v70, v21
	v_fma_f32 v24, -v230, v70, v24
	v_fma_f32 v25, -v150, v70, v25
	v_fma_f32 v20, -v143, v71, v20
	v_fma_f32 v21, -v147, v71, v21
	v_fma_f32 v24, -v231, v71, v24
	v_fma_f32 v25, -v151, v71, v25
	v_fma_f32 v20, -v144, v112, v20
	v_fma_f32 v21, -v148, v112, v21
	v_fma_f32 v24, -v232, v112, v24
	v_fma_f32 v25, -v152, v112, v25
	v_fma_f32 v20, -v145, v113, v20
	ds_read_b128 v[142:145], v109 offset:11408
	v_fma_f32 v21, -v149, v113, v21
	ds_read_b128 v[146:149], v109 offset:11664
	v_fma_f32 v24, -v233, v113, v24
	ds_read_b128 v[230:233], v109 offset:11920
	v_fma_f32 v25, -v153, v113, v25
	ds_read_b128 v[150:153], v109 offset:12176
	s_waitcnt lgkmcnt(4)
; #define LAS __attribute__((address_space(3)))
; __device__ __forceinline__ void gdn_local_unit(LAS unsigned char* lds, const GdnP& P, int unit, const int tid, const int pf) {
;     ...
;         for (int c = 1; c < 64; ++c) { f32x2 sp = (f32x2){sol2[c >> 1][c & 1], 0.f};
; #pragma unroll
;             for (int jb = 0; jb <= (c - 1) / 4; ++jb) { const f32x4 m4 = *(const LAS f32x4*)(Ms + c * 64 + 4 * jb);
;                 sp -= (f32x2){m4.x, m4.y} * sol2[2 * jb]; sp -= (f32x2){m4.z, m4.w} * sol2[2 * jb + 1]; }
;             sol2[c >> 1][c & 1] = sp.x + sp.y; }
	v_fma_f32 v20, -v220, v116, v20
	v_fma_f32 v21, -v158, v116, v21
	v_fma_f32 v24, -v154, v116, v24
	v_fma_f32 v25, -v234, v116, v25
	v_fma_f32 v20, -v221, v117, v20
	v_fma_f32 v21, -v159, v117, v21
	v_fma_f32 v24, -v155, v117, v24
	v_fma_f32 v25, -v235, v117, v25
	v_fma_f32 v20, -v222, v122, v20
	v_fma_f32 v21, -v160, v122, v21
	v_fma_f32 v24, -v156, v122, v24
	v_fma_f32 v25, -v236, v122, v25
	v_fma_f32 v20, -v223, v123, v20
	ds_read_b128 v[220:223], v109 offset:11424
	v_fma_f32 v21, -v161, v123, v21
	ds_read_b128 v[158:161], v109 offset:11680
	v_fma_f32 v24, -v157, v123, v24
	ds_read_b128 v[154:157], v109 offset:11936
	v_fma_f32 v25, -v237, v123, v25
	ds_read_b128 v[234:237], v109 offset:12192
	s_waitcnt lgkmcnt(4)
	v_fma_f32 v20, -v142, v128, v20
	v_fma_f32 v21, -v146, v128, v21
	v_fma_f32 v24, -v230, v128, v24
	v_fma_f32 v25, -v150, v128, v25
	v_fma_f32 v20, -v143, v129, v20
	v_fma_f32 v21, -v147, v129, v21
	v_fma_f32 v24, -v231, v129, v24
	v_fma_f32 v25, -v151, v129, v25
	v_fma_f32 v20, -v144, v134, v20
	v_fma_f32 v21, -v148, v134, v21
	v_fma_f32 v24, -v232, v134, v24
	v_fma_f32 v25, -v152, v134, v25
	v_fma_f32 v20, -v145, v135, v20
	ds_read_b128 v[142:145], v109 offset:11696
	v_fma_f32 v21, -v149, v135, v21
	ds_read_b128 v[146:149], v109 offset:12288
	v_fma_f32 v24, -v233, v135, v24
	ds_read_b128 v[230:233], v109 offset:12544
	v_fma_f32 v25, -v153, v135, v25
	ds_read_b128 v[150:153], v109 offset:12800
	s_waitcnt lgkmcnt(4)
	v_fma_f32 v20, -v220, v140, v20
	v_fma_f32 v21, -v158, v140, v21
	v_fma_f32 v24, -v154, v140, v24
	v_fma_f32 v25, -v234, v140, v25
	v_fma_f32 v20, -v221, v141, v20
	v_fma_f32 v21, -v159, v141, v21
	v_fma_f32 v24, -v155, v141, v24
	v_fma_f32 v25, -v235, v141, v25
	v_fma_f32 v20, -v222, v138, v20
	v_fma_f32 v21, -v160, v138, v21
	v_fma_f32 v24, -v156, v138, v24
	v_fma_f32 v25, -v236, v138, v25
	v_fma_f32 v132, -v223, v139, v20
	ds_read_b128 v[220:223], v109 offset:11952
	v_fma_f32 v21, -v161, v139, v21
	ds_read_b128 v[158:161], v109 offset:13056
	v_fma_f32 v24, -v157, v139, v24
	ds_read_b128 v[154:157], v109 offset:12208
	v_fma_f32 v25, -v237, v139, v25
	ds_read_b128 v[234:237], v109 offset:12304
	s_waitcnt lgkmcnt(4)
	v_fma_f32 v133, -v142, v132, v21
	ds_read_b128 v[142:145], v109 offset:12560
	v_fma_f32 v10, -v146, v0, v118
	v_fma_f32 v11, -v230, v0, v119
	v_fma_f32 v16, -v150, v0, v74
	s_waitcnt lgkmcnt(3)
	v_fma_f32 v24, -v220, v132, v24
	v_fma_f32 v17, -v158, v0, v75
	v_fma_f32 v10, -v147, v1, v10
	v_fma_f32 v11, -v231, v1, v11
	s_waitcnt lgkmcnt(2)
	v_fma_f32 v25, -v154, v132, v25
	v_fma_f32 v16, -v151, v1, v16
	v_fma_f32 v17, -v159, v1, v17
	v_fma_f32 v10, -v148, v8, v10
	v_fma_f32 v124, -v221, v133, v24
	ds_read_b128 v[220:223], v109 offset:12816
	v_fma_f32 v11, -v232, v8, v11
	v_fma_f32 v16, -v152, v8, v16
	v_fma_f32 v17, -v160, v8, v17
	v_fma_f32 v25, -v155, v133, v25
	v_fma_f32 v10, -v149, v9, v10
	ds_read_b128 v[146:149], v109 offset:13072
	v_fma_f32 v11, -v233, v9, v11
	ds_read_b128 v[230:233], v109 offset:12320
	v_fma_f32 v16, -v153, v9, v16
	ds_read_b128 v[150:153], v109 offset:12576
	v_fma_f32 v125, -v156, v124, v25
	ds_read_b128 v[154:157], v109 offset:12832
	v_fma_f32 v17, -v161, v9, v17
	ds_read_b128 v[158:161], v109 offset:13088
	s_waitcnt lgkmcnt(4)
	v_fma_f32 v10, -v234, v14, v10
	v_fma_f32 v11, -v142, v14, v11
	v_fma_f32 v16, -v220, v14, v16
	v_fma_f32 v17, -v146, v14, v17
	v_fma_f32 v10, -v235, v15, v10
	v_fma_f32 v11, -v143, v15, v11
	v_fma_f32 v16, -v221, v15, v16
	v_fma_f32 v17, -v147, v15, v17
	v_fma_f32 v10, -v236, v18, v10
	v_fma_f32 v11, -v144, v18, v11
	v_fma_f32 v16, -v222, v18, v16
	v_fma_f32 v17, -v148, v18, v17
	v_fma_f32 v10, -v237, v19, v10
	ds_read_b128 v[234:237], v109 offset:12336
	v_fma_f32 v11, -v145, v19, v11
	ds_read_b128 v[142:145], v109 offset:12592
	v_fma_f32 v16, -v223, v19, v16
	ds_read_b128 v[220:223], v109 offset:12848
	v_fma_f32 v17, -v149, v19, v17
	ds_read_b128 v[146:149], v109 offset:13104
	s_waitcnt lgkmcnt(4)
	v_fma_f32 v10, -v230, v22, v10
	v_fma_f32 v11, -v150, v22, v11
	v_fma_f32 v16, -v154, v22, v16
	v_fma_f32 v17, -v158, v22, v17
	v_fma_f32 v10, -v231, v23, v10
	v_fma_f32 v11, -v151, v23, v11
	v_fma_f32 v16, -v155, v23, v16
	v_fma_f32 v17, -v159, v23, v17
	v_fma_f32 v10, -v232, v26, v10
	v_fma_f32 v11, -v152, v26, v11
	v_fma_f32 v16, -v156, v26, v16
	v_fma_f32 v17, -v160, v26, v17
	v_fma_f32 v10, -v233, v27, v10
	ds_read_b128 v[230:233], v109 offset:12352
	v_fma_f32 v11, -v153, v27, v11
	ds_read_b128 v[150:153], v109 offset:12608
	v_fma_f32 v16, -v157, v27, v16
	ds_read_b128 v[154:157], v109 offset:12864
	v_fma_f32 v17, -v161, v27, v17
	ds_read_b128 v[158:161], v109 offset:13120
	s_waitcnt lgkmcnt(4)
	v_fma_f32 v10, -v234, v30, v10
	v_fma_f32 v11, -v142, v30, v11
	v_fma_f32 v16, -v220, v30, v16
	v_fma_f32 v17, -v146, v30, v17
	v_fma_f32 v10, -v235, v31, v10
	v_fma_f32 v11, -v143, v31, v11
	v_fma_f32 v16, -v221, v31, v16
	v_fma_f32 v17, -v147, v31, v17
	v_fma_f32 v10, -v236, v36, v10
	v_fma_f32 v11, -v144, v36, v11
	v_fma_f32 v16, -v222, v36, v16
	v_fma_f32 v17, -v148, v36, v17
	v_fma_f32 v10, -v237, v37, v10
	ds_read_b128 v[234:237], v109 offset:12368
	v_fma_f32 v11, -v145, v37, v11
	ds_read_b128 v[142:145], v109 offset:12624
	v_fma_f32 v16, -v223, v37, v16
	ds_read_b128 v[220:223], v109 offset:12880
	v_fma_f32 v17, -v149, v37, v17
	ds_read_b128 v[146:149], v109 offset:13136
	s_waitcnt lgkmcnt(4)
; #define LAS __attribute__((address_space(3)))
; __device__ __forceinline__ void gdn_local_unit(LAS unsigned char* lds, const GdnP& P, int unit, const int tid, const int pf) {
;     ...
;         for (int c = 1; c < 64; ++c) { f32x2 sp = (f32x2){sol2[c >> 1][c & 1], 0.f};
; #pragma unroll
;             for (int jb = 0; jb <= (c - 1) / 4; ++jb) { const f32x4 m4 = *(const LAS f32x4*)(Ms + c * 64 + 4 * jb);
;                 sp -= (f32x2){m4.x, m4.y} * sol2[2 * jb]; sp -= (f32x2){m4.z, m4.w} * sol2[2 * jb + 1]; }
;             sol2[c >> 1][c & 1] = sp.x + sp.y; }
	v_fma_f32 v10, -v230, v40, v10
	v_fma_f32 v11, -v150, v40, v11
	v_fma_f32 v16, -v154, v40, v16
	v_fma_f32 v17, -v158, v40, v17
	v_fma_f32 v10, -v231, v41, v10
	v_fma_f32 v11, -v151, v41, v11
	v_fma_f32 v16, -v155, v41, v16
	v_fma_f32 v17, -v159, v41, v17
	v_fma_f32 v10, -v232, v44, v10
	v_fma_f32 v11, -v152, v44, v11
	v_fma_f32 v16, -v156, v44, v16
	v_fma_f32 v17, -v160, v44, v17
	v_fma_f32 v10, -v233, v45, v10
	ds_read_b128 v[230:233], v109 offset:12384
	v_fma_f32 v11, -v153, v45, v11
	ds_read_b128 v[150:153], v109 offset:12640
	v_fma_f32 v16, -v157, v45, v16
	ds_read_b128 v[154:157], v109 offset:12896
	v_fma_f32 v17, -v161, v45, v17
	ds_read_b128 v[158:161], v109 offset:13152
	s_waitcnt lgkmcnt(4)
	v_fma_f32 v10, -v234, v50, v10
	v_fma_f32 v11, -v142, v50, v11
	v_fma_f32 v16, -v220, v50, v16
	v_fma_f32 v17, -v146, v50, v17
	v_fma_f32 v10, -v235, v51, v10
	v_fma_f32 v11, -v143, v51, v11
	v_fma_f32 v16, -v221, v51, v16
	v_fma_f32 v17, -v147, v51, v17
	v_fma_f32 v10, -v236, v54, v10
	v_fma_f32 v11, -v144, v54, v11
	v_fma_f32 v16, -v222, v54, v16
	v_fma_f32 v17, -v148, v54, v17
	v_fma_f32 v10, -v237, v55, v10
	ds_read_b128 v[234:237], v109 offset:12400
	v_fma_f32 v11, -v145, v55, v11
	ds_read_b128 v[142:145], v109 offset:12656
	v_fma_f32 v16, -v223, v55, v16
	ds_read_b128 v[220:223], v109 offset:12912
	v_fma_f32 v17, -v149, v55, v17
	ds_read_b128 v[146:149], v109 offset:13168
	s_waitcnt lgkmcnt(4)
	v_fma_f32 v10, -v230, v60, v10
	v_fma_f32 v11, -v150, v60, v11
	v_fma_f32 v16, -v154, v60, v16
	v_fma_f32 v17, -v158, v60, v17
	v_fma_f32 v10, -v231, v61, v10
	v_fma_f32 v11, -v151, v61, v11
	v_fma_f32 v16, -v155, v61, v16
	v_fma_f32 v17, -v159, v61, v17
	v_fma_f32 v10, -v232, v64, v10
	v_fma_f32 v11, -v152, v64, v11
	v_fma_f32 v16, -v156, v64, v16
	v_fma_f32 v17, -v160, v64, v17
	v_fma_f32 v10, -v233, v65, v10
	ds_read_b128 v[230:233], v109 offset:12416
	v_fma_f32 v11, -v153, v65, v11
	ds_read_b128 v[150:153], v109 offset:12672
	v_fma_f32 v16, -v157, v65, v16
	ds_read_b128 v[154:157], v109 offset:12928
	v_fma_f32 v17, -v161, v65, v17
	ds_read_b128 v[158:161], v109 offset:13184
	s_waitcnt lgkmcnt(4)
	v_fma_f32 v10, -v234, v70, v10
	v_fma_f32 v11, -v142, v70, v11
	v_fma_f32 v16, -v220, v70, v16
	v_fma_f32 v17, -v146, v70, v17
	v_fma_f32 v10, -v235, v71, v10
	v_fma_f32 v11, -v143, v71, v11
	v_fma_f32 v16, -v221, v71, v16
	v_fma_f32 v17, -v147, v71, v17
	v_fma_f32 v10, -v236, v112, v10
	v_fma_f32 v11, -v144, v112, v11
	v_fma_f32 v16, -v222, v112, v16
	v_fma_f32 v17, -v148, v112, v17
	v_fma_f32 v10, -v237, v113, v10
	ds_read_b128 v[234:237], v109 offset:12432
	v_fma_f32 v11, -v145, v113, v11
	ds_read_b128 v[142:145], v109 offset:12688
	v_fma_f32 v16, -v223, v113, v16
	ds_read_b128 v[220:223], v109 offset:12944
	v_fma_f32 v17, -v149, v113, v17
	ds_read_b128 v[146:149], v109 offset:13200
	s_waitcnt lgkmcnt(4)
	v_fma_f32 v10, -v230, v116, v10
	v_fma_f32 v11, -v150, v116, v11
	v_fma_f32 v16, -v154, v116, v16
	v_fma_f32 v17, -v158, v116, v17
	v_fma_f32 v10, -v231, v117, v10
	v_fma_f32 v11, -v151, v117, v11
	v_fma_f32 v16, -v155, v117, v16
	v_fma_f32 v17, -v159, v117, v17
	v_fma_f32 v10, -v232, v122, v10
	v_fma_f32 v11, -v152, v122, v11
	v_fma_f32 v16, -v156, v122, v16
	v_fma_f32 v17, -v160, v122, v17
	v_fma_f32 v10, -v233, v123, v10
	ds_read_b128 v[230:233], v109 offset:12448
	v_fma_f32 v11, -v153, v123, v11
	ds_read_b128 v[150:153], v109 offset:12704
	v_fma_f32 v16, -v157, v123, v16
	ds_read_b128 v[154:157], v109 offset:12960
	v_fma_f32 v17, -v161, v123, v17
	ds_read_b128 v[158:161], v109 offset:13216
	s_waitcnt lgkmcnt(4)
	v_fma_f32 v10, -v234, v128, v10
	v_fma_f32 v11, -v142, v128, v11
	v_fma_f32 v16, -v220, v128, v16
	v_fma_f32 v17, -v146, v128, v17
	v_fma_f32 v10, -v235, v129, v10
	v_fma_f32 v11, -v143, v129, v11
	v_fma_f32 v16, -v221, v129, v16
	v_fma_f32 v17, -v147, v129, v17
	v_fma_f32 v10, -v236, v134, v10
	v_fma_f32 v11, -v144, v134, v11
	v_fma_f32 v16, -v222, v134, v16
	v_fma_f32 v17, -v148, v134, v17
	v_fma_f32 v10, -v237, v135, v10
	ds_read_b128 v[234:237], v109 offset:12464
	v_fma_f32 v11, -v145, v135, v11
	ds_read_b128 v[142:145], v109 offset:12720
	v_fma_f32 v16, -v223, v135, v16
	ds_read_b128 v[220:223], v109 offset:12976
	v_fma_f32 v17, -v149, v135, v17
	ds_read_b128 v[146:149], v109 offset:13232
	s_waitcnt lgkmcnt(4)
	v_fma_f32 v10, -v230, v140, v10
	v_fma_f32 v11, -v150, v140, v11
	v_fma_f32 v16, -v154, v140, v16
	v_fma_f32 v17, -v158, v140, v17
	v_fma_f32 v10, -v231, v141, v10
	v_fma_f32 v11, -v151, v141, v11
	v_fma_f32 v16, -v155, v141, v16
	v_fma_f32 v17, -v159, v141, v17
	v_fma_f32 v10, -v232, v138, v10
	v_fma_f32 v11, -v152, v138, v11
	v_fma_f32 v16, -v156, v138, v16
	v_fma_f32 v17, -v160, v138, v17
	v_fma_f32 v10, -v233, v139, v10
	ds_read_b128 v[230:233], v109 offset:12736
	v_fma_f32 v11, -v153, v139, v11
	ds_read_b128 v[150:153], v109 offset:13312
	v_fma_f32 v16, -v157, v139, v16
	ds_read_b128 v[154:157], v109 offset:13568
	v_fma_f32 v17, -v161, v139, v17
	ds_read_b128 v[158:161], v109 offset:13824
	s_waitcnt lgkmcnt(4)
	v_fma_f32 v10, -v234, v132, v10
	v_fma_f32 v11, -v142, v132, v11
	v_fma_f32 v16, -v220, v132, v16
	v_fma_f32 v17, -v146, v132, v17
	v_fma_f32 v10, -v235, v133, v10
	v_fma_f32 v11, -v143, v133, v11
	v_fma_f32 v16, -v221, v133, v16
	v_fma_f32 v17, -v147, v133, v17
	v_fma_f32 v10, -v236, v124, v10
	v_fma_f32 v11, -v144, v124, v11
	v_fma_f32 v16, -v222, v124, v16
	v_fma_f32 v17, -v148, v124, v17
	v_fma_f32 v118, -v237, v125, v10
	ds_read_b128 v[234:237], v109 offset:12992
	v_fma_f32 v11, -v145, v125, v11
	ds_read_b128 v[142:145], v109 offset:14080
	v_fma_f32 v16, -v223, v125, v16
	ds_read_b128 v[220:223], v109 offset:13248
	v_fma_f32 v17, -v149, v125, v17
	ds_read_b128 v[146:149], v109 offset:13328
	s_waitcnt lgkmcnt(4)
; #define LAS __attribute__((address_space(3)))
; __device__ __forceinline__ void gdn_local_unit(LAS unsigned char* lds, const GdnP& P, int unit, const int tid, const int pf) {
;     ...
;         for (int c = 1; c < 64; ++c) { f32x2 sp = (f32x2){sol2[c >> 1][c & 1], 0.f};
; #pragma unroll
;             for (int jb = 0; jb <= (c - 1) / 4; ++jb) { const f32x4 m4 = *(const LAS f32x4*)(Ms + c * 64 + 4 * jb);
;                 sp -= (f32x2){m4.x, m4.y} * sol2[2 * jb]; sp -= (f32x2){m4.z, m4.w} * sol2[2 * jb + 1]; }
;             sol2[c >> 1][c & 1] = sp.x + sp.y; }
	v_fma_f32 v119, -v230, v118, v11
	ds_read_b128 v[230:233], v109 offset:13584
	v_fma_f32 v20, -v150, v0, v66
	v_fma_f32 v21, -v154, v0, v67
	v_fma_f32 v24, -v158, v0, v56
	s_waitcnt lgkmcnt(3)
	v_fma_f32 v16, -v234, v118, v16
	v_fma_f32 v25, -v142, v0, v57
	v_fma_f32 v20, -v151, v1, v20
	v_fma_f32 v21, -v155, v1, v21
	s_waitcnt lgkmcnt(2)
	v_fma_f32 v17, -v220, v118, v17
	v_fma_f32 v24, -v159, v1, v24
	v_fma_f32 v25, -v143, v1, v25
	v_fma_f32 v20, -v152, v8, v20
	v_fma_f32 v74, -v235, v119, v16
	ds_read_b128 v[234:237], v109 offset:13840
	v_fma_f32 v21, -v156, v8, v21
	v_fma_f32 v24, -v160, v8, v24
	v_fma_f32 v25, -v144, v8, v25
	v_fma_f32 v17, -v221, v119, v17
	v_fma_f32 v20, -v153, v9, v20
	ds_read_b128 v[150:153], v109 offset:14096
	v_fma_f32 v21, -v157, v9, v21
	ds_read_b128 v[154:157], v109 offset:13344
	v_fma_f32 v24, -v161, v9, v24
	ds_read_b128 v[158:161], v109 offset:13600
	v_fma_f32 v75, -v222, v74, v17
	ds_read_b128 v[220:223], v109 offset:13856
	v_fma_f32 v25, -v145, v9, v25
	ds_read_b128 v[142:145], v109 offset:14112
	s_waitcnt lgkmcnt(4)
	v_fma_f32 v20, -v146, v14, v20
	v_fma_f32 v21, -v230, v14, v21
	v_fma_f32 v24, -v234, v14, v24
	v_fma_f32 v25, -v150, v14, v25
	v_fma_f32 v20, -v147, v15, v20
	v_fma_f32 v21, -v231, v15, v21
	v_fma_f32 v24, -v235, v15, v24
	v_fma_f32 v25, -v151, v15, v25
	v_fma_f32 v20, -v148, v18, v20
	v_fma_f32 v21, -v232, v18, v21
	v_fma_f32 v24, -v236, v18, v24
	v_fma_f32 v25, -v152, v18, v25
	v_fma_f32 v20, -v149, v19, v20
	ds_read_b128 v[146:149], v109 offset:13360
	v_fma_f32 v21, -v233, v19, v21
	ds_read_b128 v[230:233], v109 offset:13616
	v_fma_f32 v24, -v237, v19, v24
	ds_read_b128 v[234:237], v109 offset:13872
	v_fma_f32 v25, -v153, v19, v25
	ds_read_b128 v[150:153], v109 offset:14128
	s_waitcnt lgkmcnt(4)
	v_fma_f32 v20, -v154, v22, v20
	v_fma_f32 v21, -v158, v22, v21
	v_fma_f32 v24, -v220, v22, v24
	v_fma_f32 v25, -v142, v22, v25
	v_fma_f32 v20, -v155, v23, v20
	v_fma_f32 v21, -v159, v23, v21
	v_fma_f32 v24, -v221, v23, v24
	v_fma_f32 v25, -v143, v23, v25
	v_fma_f32 v20, -v156, v26, v20
	v_fma_f32 v21, -v160, v26, v21
	v_fma_f32 v24, -v222, v26, v24
	v_fma_f32 v25, -v144, v26, v25
	v_fma_f32 v20, -v157, v27, v20
	ds_read_b128 v[154:157], v109 offset:13376
	v_fma_f32 v21, -v161, v27, v21
	ds_read_b128 v[158:161], v109 offset:13632
	v_fma_f32 v24, -v223, v27, v24
	ds_read_b128 v[220:223], v109 offset:13888
	v_fma_f32 v25, -v145, v27, v25
	ds_read_b128 v[142:145], v109 offset:14144
	s_waitcnt lgkmcnt(4)
	v_fma_f32 v20, -v146, v30, v20
	v_fma_f32 v21, -v230, v30, v21
	v_fma_f32 v24, -v234, v30, v24
	v_fma_f32 v25, -v150, v30, v25
	v_fma_f32 v20, -v147, v31, v20
	v_fma_f32 v21, -v231, v31, v21
	v_fma_f32 v24, -v235, v31, v24
	v_fma_f32 v25, -v151, v31, v25
	v_fma_f32 v20, -v148, v36, v20
	v_fma_f32 v21, -v232, v36, v21
	v_fma_f32 v24, -v236, v36, v24
	v_fma_f32 v25, -v152, v36, v25
	v_fma_f32 v20, -v149, v37, v20
	ds_read_b128 v[146:149], v109 offset:13392
	v_fma_f32 v21, -v233, v37, v21
	ds_read_b128 v[230:233], v109 offset:13648
	v_fma_f32 v24, -v237, v37, v24
	ds_read_b128 v[234:237], v109 offset:13904
	v_fma_f32 v25, -v153, v37, v25
	ds_read_b128 v[150:153], v109 offset:14160
	s_waitcnt lgkmcnt(4)
	v_fma_f32 v20, -v154, v40, v20
	v_fma_f32 v21, -v158, v40, v21
	v_fma_f32 v24, -v220, v40, v24
	v_fma_f32 v25, -v142, v40, v25
	v_fma_f32 v20, -v155, v41, v20
	v_fma_f32 v21, -v159, v41, v21
	v_fma_f32 v24, -v221, v41, v24
	v_fma_f32 v25, -v143, v41, v25
	v_fma_f32 v20, -v156, v44, v20
	v_fma_f32 v21, -v160, v44, v21
	v_fma_f32 v24, -v222, v44, v24
	v_fma_f32 v25, -v144, v44, v25
	v_fma_f32 v20, -v157, v45, v20
	ds_read_b128 v[154:157], v109 offset:13408
	v_fma_f32 v21, -v161, v45, v21
	ds_read_b128 v[158:161], v109 offset:13664
	v_fma_f32 v24, -v223, v45, v24
	ds_read_b128 v[220:223], v109 offset:13920
	v_fma_f32 v25, -v145, v45, v25
	ds_read_b128 v[142:145], v109 offset:14176
	s_waitcnt lgkmcnt(4)
	v_fma_f32 v20, -v146, v50, v20
	v_fma_f32 v21, -v230, v50, v21
	v_fma_f32 v24, -v234, v50, v24
	v_fma_f32 v25, -v150, v50, v25
	v_fma_f32 v20, -v147, v51, v20
	v_fma_f32 v21, -v231, v51, v21
	v_fma_f32 v24, -v235, v51, v24
	v_fma_f32 v25, -v151, v51, v25
	v_fma_f32 v20, -v148, v54, v20
	v_fma_f32 v21, -v232, v54, v21
	v_fma_f32 v24, -v236, v54, v24
	v_fma_f32 v25, -v152, v54, v25
	v_fma_f32 v20, -v149, v55, v20
	ds_read_b128 v[146:149], v109 offset:13424
	v_fma_f32 v21, -v233, v55, v21
	ds_read_b128 v[230:233], v109 offset:13680
	v_fma_f32 v24, -v237, v55, v24
	ds_read_b128 v[234:237], v109 offset:13936
	v_fma_f32 v25, -v153, v55, v25
	ds_read_b128 v[150:153], v109 offset:14192
	s_waitcnt lgkmcnt(4)
	v_fma_f32 v20, -v154, v60, v20
	v_fma_f32 v21, -v158, v60, v21
	v_fma_f32 v24, -v220, v60, v24
	v_fma_f32 v25, -v142, v60, v25
	v_fma_f32 v20, -v155, v61, v20
	v_fma_f32 v21, -v159, v61, v21
	v_fma_f32 v24, -v221, v61, v24
	v_fma_f32 v25, -v143, v61, v25
	v_fma_f32 v20, -v156, v64, v20
	v_fma_f32 v21, -v160, v64, v21
	v_fma_f32 v24, -v222, v64, v24
	v_fma_f32 v25, -v144, v64, v25
	v_fma_f32 v20, -v157, v65, v20
	ds_read_b128 v[154:157], v109 offset:13440
	v_fma_f32 v21, -v161, v65, v21
	ds_read_b128 v[158:161], v109 offset:13696
	v_fma_f32 v24, -v223, v65, v24
	ds_read_b128 v[220:223], v109 offset:13952
	v_fma_f32 v25, -v145, v65, v25
	ds_read_b128 v[142:145], v109 offset:14208
	s_waitcnt lgkmcnt(4)
; #define LAS __attribute__((address_space(3)))
; __device__ __forceinline__ void gdn_local_unit(LAS unsigned char* lds, const GdnP& P, int unit, const int tid, const int pf) {
;     ...
;         for (int c = 1; c < 64; ++c) { f32x2 sp = (f32x2){sol2[c >> 1][c & 1], 0.f};
; #pragma unroll
;             for (int jb = 0; jb <= (c - 1) / 4; ++jb) { const f32x4 m4 = *(const LAS f32x4*)(Ms + c * 64 + 4 * jb);
;                 sp -= (f32x2){m4.x, m4.y} * sol2[2 * jb]; sp -= (f32x2){m4.z, m4.w} * sol2[2 * jb + 1]; }
;             sol2[c >> 1][c & 1] = sp.x + sp.y; }
	v_fma_f32 v20, -v146, v70, v20
	v_fma_f32 v21, -v230, v70, v21
	v_fma_f32 v24, -v234, v70, v24
	v_fma_f32 v25, -v150, v70, v25
	v_fma_f32 v20, -v147, v71, v20
	v_fma_f32 v21, -v231, v71, v21
	v_fma_f32 v24, -v235, v71, v24
	v_fma_f32 v25, -v151, v71, v25
	v_fma_f32 v20, -v148, v112, v20
	v_fma_f32 v21, -v232, v112, v21
	v_fma_f32 v24, -v236, v112, v24
	v_fma_f32 v25, -v152, v112, v25
	v_fma_f32 v20, -v149, v113, v20
	ds_read_b128 v[146:149], v109 offset:13456
	v_fma_f32 v21, -v233, v113, v21
	ds_read_b128 v[230:233], v109 offset:13712
	v_fma_f32 v24, -v237, v113, v24
	ds_read_b128 v[234:237], v109 offset:13968
	v_fma_f32 v25, -v153, v113, v25
	ds_read_b128 v[150:153], v109 offset:14224
	s_waitcnt lgkmcnt(4)
	v_fma_f32 v20, -v154, v116, v20
	v_fma_f32 v21, -v158, v116, v21
	v_fma_f32 v24, -v220, v116, v24
	v_fma_f32 v25, -v142, v116, v25
	v_fma_f32 v20, -v155, v117, v20
	v_fma_f32 v21, -v159, v117, v21
	v_fma_f32 v24, -v221, v117, v24
	v_fma_f32 v25, -v143, v117, v25
	v_fma_f32 v20, -v156, v122, v20
	v_fma_f32 v21, -v160, v122, v21
	v_fma_f32 v24, -v222, v122, v24
	v_fma_f32 v25, -v144, v122, v25
	v_fma_f32 v20, -v157, v123, v20
	ds_read_b128 v[154:157], v109 offset:13472
	v_fma_f32 v21, -v161, v123, v21
	ds_read_b128 v[158:161], v109 offset:13728
	v_fma_f32 v24, -v223, v123, v24
	ds_read_b128 v[220:223], v109 offset:13984
	v_fma_f32 v25, -v145, v123, v25
	ds_read_b128 v[142:145], v109 offset:14240
	s_waitcnt lgkmcnt(4)
	v_fma_f32 v20, -v146, v128, v20
	v_fma_f32 v21, -v230, v128, v21
	v_fma_f32 v24, -v234, v128, v24
	v_fma_f32 v25, -v150, v128, v25
	v_fma_f32 v20, -v147, v129, v20
	v_fma_f32 v21, -v231, v129, v21
	v_fma_f32 v24, -v235, v129, v24
	v_fma_f32 v25, -v151, v129, v25
	v_fma_f32 v20, -v148, v134, v20
	v_fma_f32 v21, -v232, v134, v21
	v_fma_f32 v24, -v236, v134, v24
	v_fma_f32 v25, -v152, v134, v25
	v_fma_f32 v20, -v149, v135, v20
	ds_read_b128 v[146:149], v109 offset:13488
	v_fma_f32 v21, -v233, v135, v21
	ds_read_b128 v[230:233], v109 offset:13744
	v_fma_f32 v24, -v237, v135, v24
	ds_read_b128 v[234:237], v109 offset:14000
	v_fma_f32 v25, -v153, v135, v25
	ds_read_b128 v[150:153], v109 offset:14256
	s_waitcnt lgkmcnt(4)
	v_fma_f32 v20, -v154, v140, v20
	v_fma_f32 v21, -v158, v140, v21
	v_fma_f32 v24, -v220, v140, v24
	v_fma_f32 v25, -v142, v140, v25
	v_fma_f32 v20, -v155, v141, v20
	v_fma_f32 v21, -v159, v141, v21
	v_fma_f32 v24, -v221, v141, v24
	v_fma_f32 v25, -v143, v141, v25
	v_fma_f32 v20, -v156, v138, v20
	v_fma_f32 v21, -v160, v138, v21
	v_fma_f32 v24, -v222, v138, v24
	v_fma_f32 v25, -v144, v138, v25
	v_fma_f32 v20, -v157, v139, v20
	ds_read_b128 v[154:157], v109 offset:13504
	v_fma_f32 v21, -v161, v139, v21
	ds_read_b128 v[158:161], v109 offset:13760
	v_fma_f32 v24, -v223, v139, v24
	ds_read_b128 v[220:223], v109 offset:14016
	v_fma_f32 v25, -v145, v139, v25
	ds_read_b128 v[142:145], v109 offset:14272
	s_waitcnt lgkmcnt(4)
	v_fma_f32 v20, -v146, v132, v20
	v_fma_f32 v21, -v230, v132, v21
	v_fma_f32 v24, -v234, v132, v24
	v_fma_f32 v25, -v150, v132, v25
	v_fma_f32 v20, -v147, v133, v20
	v_fma_f32 v21, -v231, v133, v21
	v_fma_f32 v24, -v235, v133, v24
	v_fma_f32 v25, -v151, v133, v25
	v_fma_f32 v20, -v148, v124, v20
	v_fma_f32 v21, -v232, v124, v21
	v_fma_f32 v24, -v236, v124, v24
	v_fma_f32 v25, -v152, v124, v25
	v_fma_f32 v20, -v149, v125, v20
	ds_read_b128 v[146:149], v109 offset:13776
	v_fma_f32 v21, -v233, v125, v21
	ds_read_b128 v[230:233], v109 offset:14336
	v_fma_f32 v24, -v237, v125, v24
	ds_read_b128 v[234:237], v109 offset:14592
	v_fma_f32 v25, -v153, v125, v25
	ds_read_b128 v[150:153], v109 offset:14848
	s_waitcnt lgkmcnt(4)
	v_fma_f32 v20, -v154, v118, v20
	v_fma_f32 v21, -v158, v118, v21
	v_fma_f32 v24, -v220, v118, v24
	v_fma_f32 v25, -v142, v118, v25
	v_fma_f32 v20, -v155, v119, v20
	v_fma_f32 v21, -v159, v119, v21
	v_fma_f32 v24, -v221, v119, v24
	v_fma_f32 v25, -v143, v119, v25
	v_fma_f32 v20, -v156, v74, v20
	v_fma_f32 v21, -v160, v74, v21
	v_fma_f32 v24, -v222, v74, v24
	v_fma_f32 v25, -v144, v74, v25
	v_fma_f32 v66, -v157, v75, v20
	ds_read_b128 v[154:157], v109 offset:14032
	v_fma_f32 v21, -v161, v75, v21
	ds_read_b128 v[158:161], v109 offset:15104
	v_fma_f32 v24, -v223, v75, v24
	ds_read_b128 v[220:223], v109 offset:14288
	v_fma_f32 v25, -v145, v75, v25
	ds_read_b128 v[142:145], v109 offset:14352
	s_waitcnt lgkmcnt(4)
	v_fma_f32 v67, -v146, v66, v21
	ds_read_b128 v[146:149], v109 offset:14608
	v_fma_f32 v10, -v230, v0, v46
	v_fma_f32 v11, -v234, v0, v47
	v_fma_f32 v16, -v150, v0, v32
	s_waitcnt lgkmcnt(3)
	v_fma_f32 v24, -v154, v66, v24
	v_fma_f32 v17, -v158, v0, v33
	v_fma_f32 v10, -v231, v1, v10
	v_fma_f32 v11, -v235, v1, v11
	s_waitcnt lgkmcnt(2)
	v_fma_f32 v25, -v220, v66, v25
	v_fma_f32 v16, -v151, v1, v16
	v_fma_f32 v17, -v159, v1, v17
	v_fma_f32 v10, -v232, v8, v10
	v_fma_f32 v56, -v155, v67, v24
	ds_read_b128 v[154:157], v109 offset:14864
	v_fma_f32 v11, -v236, v8, v11
	v_fma_f32 v16, -v152, v8, v16
	v_fma_f32 v17, -v160, v8, v17
	v_fma_f32 v25, -v221, v67, v25
	v_fma_f32 v10, -v233, v9, v10
	ds_read_b128 v[230:233], v109 offset:15120
	v_fma_f32 v11, -v237, v9, v11
	ds_read_b128 v[234:237], v109 offset:14368
	v_fma_f32 v16, -v153, v9, v16
	ds_read_b128 v[150:153], v109 offset:14624
	v_fma_f32 v57, -v222, v56, v25
	ds_read_b128 v[220:223], v109 offset:14880
	v_fma_f32 v17, -v161, v9, v17
	ds_read_b128 v[158:161], v109 offset:15136
	s_waitcnt lgkmcnt(4)
; #define LAS __attribute__((address_space(3)))
; __device__ __forceinline__ void gdn_local_unit(LAS unsigned char* lds, const GdnP& P, int unit, const int tid, const int pf) {
;     ...
;         for (int c = 1; c < 64; ++c) { f32x2 sp = (f32x2){sol2[c >> 1][c & 1], 0.f};
; #pragma unroll
;             for (int jb = 0; jb <= (c - 1) / 4; ++jb) { const f32x4 m4 = *(const LAS f32x4*)(Ms + c * 64 + 4 * jb);
;                 sp -= (f32x2){m4.x, m4.y} * sol2[2 * jb]; sp -= (f32x2){m4.z, m4.w} * sol2[2 * jb + 1]; }
;             sol2[c >> 1][c & 1] = sp.x + sp.y; }
	v_fma_f32 v10, -v142, v14, v10
	v_fma_f32 v11, -v146, v14, v11
	v_fma_f32 v16, -v154, v14, v16
	v_fma_f32 v17, -v230, v14, v17
	v_fma_f32 v10, -v143, v15, v10
	v_fma_f32 v11, -v147, v15, v11
	v_fma_f32 v16, -v155, v15, v16
	v_fma_f32 v17, -v231, v15, v17
	v_fma_f32 v10, -v144, v18, v10
	v_fma_f32 v11, -v148, v18, v11
	v_fma_f32 v16, -v156, v18, v16
	v_fma_f32 v17, -v232, v18, v17
	v_fma_f32 v10, -v145, v19, v10
	ds_read_b128 v[142:145], v109 offset:14384
	v_fma_f32 v11, -v149, v19, v11
	ds_read_b128 v[146:149], v109 offset:14640
	v_fma_f32 v16, -v157, v19, v16
	ds_read_b128 v[154:157], v109 offset:14896
	v_fma_f32 v17, -v233, v19, v17
	ds_read_b128 v[230:233], v109 offset:15152
	s_waitcnt lgkmcnt(4)
	v_fma_f32 v10, -v234, v22, v10
	v_fma_f32 v11, -v150, v22, v11
	v_fma_f32 v16, -v220, v22, v16
	v_fma_f32 v17, -v158, v22, v17
	v_fma_f32 v10, -v235, v23, v10
	v_fma_f32 v11, -v151, v23, v11
	v_fma_f32 v16, -v221, v23, v16
	v_fma_f32 v17, -v159, v23, v17
	v_fma_f32 v10, -v236, v26, v10
	v_fma_f32 v11, -v152, v26, v11
	v_fma_f32 v16, -v222, v26, v16
	v_fma_f32 v17, -v160, v26, v17
	v_fma_f32 v10, -v237, v27, v10
	ds_read_b128 v[234:237], v109 offset:14400
	v_fma_f32 v11, -v153, v27, v11
	ds_read_b128 v[150:153], v109 offset:14656
	v_fma_f32 v16, -v223, v27, v16
	ds_read_b128 v[220:223], v109 offset:14912
	v_fma_f32 v17, -v161, v27, v17
	ds_read_b128 v[158:161], v109 offset:15168
	s_waitcnt lgkmcnt(4)
	v_fma_f32 v10, -v142, v30, v10
	v_fma_f32 v11, -v146, v30, v11
	v_fma_f32 v16, -v154, v30, v16
	v_fma_f32 v17, -v230, v30, v17
	v_fma_f32 v10, -v143, v31, v10
	v_fma_f32 v11, -v147, v31, v11
	v_fma_f32 v16, -v155, v31, v16
	v_fma_f32 v17, -v231, v31, v17
	v_fma_f32 v10, -v144, v36, v10
	v_fma_f32 v11, -v148, v36, v11
	v_fma_f32 v16, -v156, v36, v16
	v_fma_f32 v17, -v232, v36, v17
	v_fma_f32 v10, -v145, v37, v10
	ds_read_b128 v[142:145], v109 offset:14416
	v_fma_f32 v11, -v149, v37, v11
	ds_read_b128 v[146:149], v109 offset:14672
	v_fma_f32 v16, -v157, v37, v16
	ds_read_b128 v[154:157], v109 offset:14928
	v_fma_f32 v17, -v233, v37, v17
	ds_read_b128 v[230:233], v109 offset:15184
	s_waitcnt lgkmcnt(4)
	v_fma_f32 v10, -v234, v40, v10
	v_fma_f32 v11, -v150, v40, v11
	v_fma_f32 v16, -v220, v40, v16
	v_fma_f32 v17, -v158, v40, v17
	v_fma_f32 v10, -v235, v41, v10
	v_fma_f32 v11, -v151, v41, v11
	v_fma_f32 v16, -v221, v41, v16
	v_fma_f32 v17, -v159, v41, v17
	v_fma_f32 v10, -v236, v44, v10
	v_fma_f32 v11, -v152, v44, v11
	v_fma_f32 v16, -v222, v44, v16
	v_fma_f32 v17, -v160, v44, v17
	v_fma_f32 v10, -v237, v45, v10
	ds_read_b128 v[234:237], v109 offset:14432
	v_fma_f32 v11, -v153, v45, v11
	ds_read_b128 v[150:153], v109 offset:14688
	v_fma_f32 v16, -v223, v45, v16
	ds_read_b128 v[220:223], v109 offset:14944
	v_fma_f32 v17, -v161, v45, v17
	ds_read_b128 v[158:161], v109 offset:15200
	s_waitcnt lgkmcnt(4)
	v_fma_f32 v10, -v142, v50, v10
	v_fma_f32 v11, -v146, v50, v11
	v_fma_f32 v16, -v154, v50, v16
	v_fma_f32 v17, -v230, v50, v17
	v_fma_f32 v10, -v143, v51, v10
	v_fma_f32 v11, -v147, v51, v11
	v_fma_f32 v16, -v155, v51, v16
	v_fma_f32 v17, -v231, v51, v17
	v_fma_f32 v10, -v144, v54, v10
	v_fma_f32 v11, -v148, v54, v11
	v_fma_f32 v16, -v156, v54, v16
	v_fma_f32 v17, -v232, v54, v17
	v_fma_f32 v10, -v145, v55, v10
	ds_read_b128 v[142:145], v109 offset:14448
	v_fma_f32 v11, -v149, v55, v11
	ds_read_b128 v[146:149], v109 offset:14704
	v_fma_f32 v16, -v157, v55, v16
	ds_read_b128 v[154:157], v109 offset:14960
	v_fma_f32 v17, -v233, v55, v17
	ds_read_b128 v[230:233], v109 offset:15216
	s_waitcnt lgkmcnt(4)
	v_fma_f32 v10, -v234, v60, v10
	v_fma_f32 v11, -v150, v60, v11
	v_fma_f32 v16, -v220, v60, v16
	v_fma_f32 v17, -v158, v60, v17
	v_fma_f32 v10, -v235, v61, v10
	v_fma_f32 v11, -v151, v61, v11
	v_fma_f32 v16, -v221, v61, v16
	v_fma_f32 v17, -v159, v61, v17
	v_fma_f32 v10, -v236, v64, v10
	v_fma_f32 v11, -v152, v64, v11
	v_fma_f32 v16, -v222, v64, v16
	v_fma_f32 v17, -v160, v64, v17
	v_fma_f32 v10, -v237, v65, v10
	ds_read_b128 v[234:237], v109 offset:14464
	v_fma_f32 v11, -v153, v65, v11
	ds_read_b128 v[150:153], v109 offset:14720
	v_fma_f32 v16, -v223, v65, v16
	ds_read_b128 v[220:223], v109 offset:14976
	v_fma_f32 v17, -v161, v65, v17
	ds_read_b128 v[158:161], v109 offset:15232
	s_waitcnt lgkmcnt(4)
	v_fma_f32 v10, -v142, v70, v10
	v_fma_f32 v11, -v146, v70, v11
	v_fma_f32 v16, -v154, v70, v16
	v_fma_f32 v17, -v230, v70, v17
	v_fma_f32 v10, -v143, v71, v10
	v_fma_f32 v11, -v147, v71, v11
	v_fma_f32 v16, -v155, v71, v16
	v_fma_f32 v17, -v231, v71, v17
	v_fma_f32 v10, -v144, v112, v10
	v_fma_f32 v11, -v148, v112, v11
	v_fma_f32 v16, -v156, v112, v16
	v_fma_f32 v17, -v232, v112, v17
	v_fma_f32 v10, -v145, v113, v10
	ds_read_b128 v[142:145], v109 offset:14480
	v_fma_f32 v11, -v149, v113, v11
	ds_read_b128 v[146:149], v109 offset:14736
	v_fma_f32 v16, -v157, v113, v16
	ds_read_b128 v[154:157], v109 offset:14992
	v_fma_f32 v17, -v233, v113, v17
	ds_read_b128 v[230:233], v109 offset:15248
	s_waitcnt lgkmcnt(4)
	v_fma_f32 v10, -v234, v116, v10
	v_fma_f32 v11, -v150, v116, v11
	v_fma_f32 v16, -v220, v116, v16
	v_fma_f32 v17, -v158, v116, v17
	v_fma_f32 v10, -v235, v117, v10
	v_fma_f32 v11, -v151, v117, v11
	v_fma_f32 v16, -v221, v117, v16
	v_fma_f32 v17, -v159, v117, v17
	v_fma_f32 v10, -v236, v122, v10
	v_fma_f32 v11, -v152, v122, v11
	v_fma_f32 v16, -v222, v122, v16
	v_fma_f32 v17, -v160, v122, v17
	v_fma_f32 v10, -v237, v123, v10
	ds_read_b128 v[234:237], v109 offset:14496
	v_fma_f32 v11, -v153, v123, v11
	ds_read_b128 v[150:153], v109 offset:14752
	v_fma_f32 v16, -v223, v123, v16
	ds_read_b128 v[220:223], v109 offset:15008
	v_fma_f32 v17, -v161, v123, v17
	ds_read_b128 v[158:161], v109 offset:15264
	s_waitcnt lgkmcnt(4)
; #define LAS __attribute__((address_space(3)))
; __device__ __forceinline__ void gdn_local_unit(LAS unsigned char* lds, const GdnP& P, int unit, const int tid, const int pf) {
;     ...
;         for (int c = 1; c < 64; ++c) { f32x2 sp = (f32x2){sol2[c >> 1][c & 1], 0.f};
; #pragma unroll
;             for (int jb = 0; jb <= (c - 1) / 4; ++jb) { const f32x4 m4 = *(const LAS f32x4*)(Ms + c * 64 + 4 * jb);
;                 sp -= (f32x2){m4.x, m4.y} * sol2[2 * jb]; sp -= (f32x2){m4.z, m4.w} * sol2[2 * jb + 1]; }
;             sol2[c >> 1][c & 1] = sp.x + sp.y; }
	v_fma_f32 v10, -v142, v128, v10
	v_fma_f32 v11, -v146, v128, v11
	v_fma_f32 v16, -v154, v128, v16
	v_fma_f32 v17, -v230, v128, v17
	v_fma_f32 v10, -v143, v129, v10
	v_fma_f32 v11, -v147, v129, v11
	v_fma_f32 v16, -v155, v129, v16
	v_fma_f32 v17, -v231, v129, v17
	v_fma_f32 v10, -v144, v134, v10
	v_fma_f32 v11, -v148, v134, v11
	v_fma_f32 v16, -v156, v134, v16
	v_fma_f32 v17, -v232, v134, v17
	v_fma_f32 v10, -v145, v135, v10
	ds_read_b128 v[142:145], v109 offset:14512
	v_fma_f32 v11, -v149, v135, v11
	ds_read_b128 v[146:149], v109 offset:14768
	v_fma_f32 v16, -v157, v135, v16
	ds_read_b128 v[154:157], v109 offset:15024
	v_fma_f32 v17, -v233, v135, v17
	ds_read_b128 v[230:233], v109 offset:15280
	s_waitcnt lgkmcnt(4)
	v_fma_f32 v10, -v234, v140, v10
	v_fma_f32 v11, -v150, v140, v11
	v_fma_f32 v16, -v220, v140, v16
	v_fma_f32 v17, -v158, v140, v17
	v_fma_f32 v10, -v235, v141, v10
	v_fma_f32 v11, -v151, v141, v11
	v_fma_f32 v16, -v221, v141, v16
	v_fma_f32 v17, -v159, v141, v17
	v_fma_f32 v10, -v236, v138, v10
	v_fma_f32 v11, -v152, v138, v11
	v_fma_f32 v16, -v222, v138, v16
	v_fma_f32 v17, -v160, v138, v17
	v_fma_f32 v10, -v237, v139, v10
	ds_read_b128 v[234:237], v109 offset:14528
	v_fma_f32 v11, -v153, v139, v11
	ds_read_b128 v[150:153], v109 offset:14784
	v_fma_f32 v16, -v223, v139, v16
	ds_read_b128 v[220:223], v109 offset:15040
	v_fma_f32 v17, -v161, v139, v17
	ds_read_b128 v[158:161], v109 offset:15296
	s_waitcnt lgkmcnt(4)
	v_fma_f32 v10, -v142, v132, v10
	v_fma_f32 v11, -v146, v132, v11
	v_fma_f32 v16, -v154, v132, v16
	v_fma_f32 v17, -v230, v132, v17
	v_fma_f32 v10, -v143, v133, v10
	v_fma_f32 v11, -v147, v133, v11
	v_fma_f32 v16, -v155, v133, v16
	v_fma_f32 v17, -v231, v133, v17
	v_fma_f32 v10, -v144, v124, v10
	v_fma_f32 v11, -v148, v124, v11
	v_fma_f32 v16, -v156, v124, v16
	v_fma_f32 v17, -v232, v124, v17
	v_fma_f32 v10, -v145, v125, v10
	ds_read_b128 v[142:145], v109 offset:14544
	v_fma_f32 v11, -v149, v125, v11
	ds_read_b128 v[146:149], v109 offset:14800
	v_fma_f32 v16, -v157, v125, v16
	ds_read_b128 v[154:157], v109 offset:15056
	v_fma_f32 v17, -v233, v125, v17
	ds_read_b128 v[230:233], v109 offset:15312
	s_waitcnt lgkmcnt(4)
	v_fma_f32 v10, -v234, v118, v10
	v_fma_f32 v11, -v150, v118, v11
	v_fma_f32 v16, -v220, v118, v16
	v_fma_f32 v17, -v158, v118, v17
	v_fma_f32 v10, -v235, v119, v10
	v_fma_f32 v11, -v151, v119, v11
	v_fma_f32 v16, -v221, v119, v16
	v_fma_f32 v17, -v159, v119, v17
	v_fma_f32 v10, -v236, v74, v10
	v_fma_f32 v11, -v152, v74, v11
	v_fma_f32 v16, -v222, v74, v16
	v_fma_f32 v17, -v160, v74, v17
	v_fma_f32 v10, -v237, v75, v10
	ds_read_b128 v[234:237], v109 offset:14816
	v_fma_f32 v11, -v153, v75, v11
	ds_read_b128 v[150:153], v109 offset:15360
	v_fma_f32 v16, -v223, v75, v16
	ds_read_b128 v[220:223], v109 offset:15616
	v_fma_f32 v17, -v161, v75, v17
	ds_read_b128 v[158:161], v109 offset:15872
	s_waitcnt lgkmcnt(4)
	v_fma_f32 v10, -v142, v66, v10
	v_fma_f32 v11, -v146, v66, v11
	v_fma_f32 v16, -v154, v66, v16
	v_fma_f32 v17, -v230, v66, v17
	v_fma_f32 v10, -v143, v67, v10
	v_fma_f32 v11, -v147, v67, v11
	v_fma_f32 v16, -v155, v67, v16
	v_fma_f32 v17, -v231, v67, v17
	v_fma_f32 v10, -v144, v56, v10
	v_fma_f32 v11, -v148, v56, v11
	v_fma_f32 v16, -v156, v56, v16
	v_fma_f32 v17, -v232, v56, v17
	v_fma_f32 v46, -v145, v57, v10
	ds_read_b128 v[142:145], v109 offset:15072
	v_fma_f32 v11, -v149, v57, v11
	ds_read_b128 v[146:149], v109 offset:16128
	v_fma_f32 v16, -v157, v57, v16
	ds_read_b128 v[154:157], v109 offset:15328
	v_fma_f32 v17, -v233, v57, v17
	ds_read_b128 v[230:233], v109 offset:15376
	s_waitcnt lgkmcnt(4)
	v_fma_f32 v47, -v234, v46, v11
	ds_read_b128 v[234:237], v109 offset:15632
	v_fma_f32 v20, -v150, v0, v12
	v_fma_f32 v21, -v220, v0, v13
	v_fma_f32 v24, -v158, v0, v2
	s_waitcnt lgkmcnt(3)
	v_fma_f32 v16, -v142, v46, v16
	v_fma_f32 v25, -v146, v0, v3
	v_fma_f32 v20, -v151, v1, v20
	v_fma_f32 v21, -v221, v1, v21
	s_waitcnt lgkmcnt(2)
	v_fma_f32 v17, -v154, v46, v17
	v_fma_f32 v24, -v159, v1, v24
	v_fma_f32 v25, -v147, v1, v25
	v_fma_f32 v20, -v152, v8, v20
	v_fma_f32 v32, -v143, v47, v16
	ds_read_b128 v[142:145], v109 offset:15888
	v_fma_f32 v21, -v222, v8, v21
	v_fma_f32 v24, -v160, v8, v24
	v_fma_f32 v25, -v148, v8, v25
	v_fma_f32 v17, -v155, v47, v17
	v_fma_f32 v20, -v153, v9, v20
	ds_read_b128 v[150:153], v109 offset:16144
	v_fma_f32 v21, -v223, v9, v21
	ds_read_b128 v[220:223], v109 offset:15392
	v_fma_f32 v24, -v161, v9, v24
	ds_read_b128 v[158:161], v109 offset:15648
	v_fma_f32 v33, -v156, v32, v17
	ds_read_b128 v[154:157], v109 offset:15904
	v_fma_f32 v25, -v149, v9, v25
	ds_read_b128 v[146:149], v109 offset:16160
	s_waitcnt lgkmcnt(4)
	v_fma_f32 v20, -v230, v14, v20
	v_fma_f32 v21, -v234, v14, v21
	v_fma_f32 v24, -v142, v14, v24
	v_fma_f32 v25, -v150, v14, v25
	v_fma_f32 v20, -v231, v15, v20
	v_fma_f32 v21, -v235, v15, v21
	v_fma_f32 v24, -v143, v15, v24
	v_fma_f32 v25, -v151, v15, v25
	v_fma_f32 v20, -v232, v18, v20
	v_fma_f32 v21, -v236, v18, v21
	v_fma_f32 v24, -v144, v18, v24
	v_fma_f32 v25, -v152, v18, v25
	v_fma_f32 v20, -v233, v19, v20
	ds_read_b128 v[230:233], v109 offset:15408
	v_fma_f32 v21, -v237, v19, v21
	ds_read_b128 v[234:237], v109 offset:15664
	v_fma_f32 v24, -v145, v19, v24
	ds_read_b128 v[142:145], v109 offset:15920
	v_fma_f32 v25, -v153, v19, v25
	ds_read_b128 v[150:153], v109 offset:16176
	s_waitcnt lgkmcnt(4)
; #define LAS __attribute__((address_space(3)))
; __device__ __forceinline__ void gdn_local_unit(LAS unsigned char* lds, const GdnP& P, int unit, const int tid, const int pf) {
;     ...
;         for (int c = 1; c < 64; ++c) { f32x2 sp = (f32x2){sol2[c >> 1][c & 1], 0.f};
; #pragma unroll
;             for (int jb = 0; jb <= (c - 1) / 4; ++jb) { const f32x4 m4 = *(const LAS f32x4*)(Ms + c * 64 + 4 * jb);
;                 sp -= (f32x2){m4.x, m4.y} * sol2[2 * jb]; sp -= (f32x2){m4.z, m4.w} * sol2[2 * jb + 1]; }
;             sol2[c >> 1][c & 1] = sp.x + sp.y; }
	v_fma_f32 v20, -v220, v22, v20
	v_fma_f32 v21, -v158, v22, v21
	v_fma_f32 v24, -v154, v22, v24
	v_fma_f32 v25, -v146, v22, v25
	v_fma_f32 v20, -v221, v23, v20
	v_fma_f32 v21, -v159, v23, v21
	v_fma_f32 v24, -v155, v23, v24
	v_fma_f32 v25, -v147, v23, v25
	v_fma_f32 v20, -v222, v26, v20
	v_fma_f32 v21, -v160, v26, v21
	v_fma_f32 v24, -v156, v26, v24
	v_fma_f32 v25, -v148, v26, v25
	v_fma_f32 v20, -v223, v27, v20
	ds_read_b128 v[220:223], v109 offset:15424
	v_fma_f32 v21, -v161, v27, v21
	ds_read_b128 v[158:161], v109 offset:15680
	v_fma_f32 v24, -v157, v27, v24
	ds_read_b128 v[154:157], v109 offset:15936
	v_fma_f32 v25, -v149, v27, v25
	ds_read_b128 v[146:149], v109 offset:16192
	s_waitcnt lgkmcnt(4)
	v_fma_f32 v20, -v230, v30, v20
	v_fma_f32 v21, -v234, v30, v21
	v_fma_f32 v24, -v142, v30, v24
	v_fma_f32 v25, -v150, v30, v25
	v_fma_f32 v20, -v231, v31, v20
	v_fma_f32 v21, -v235, v31, v21
	v_fma_f32 v24, -v143, v31, v24
	v_fma_f32 v25, -v151, v31, v25
	v_fma_f32 v20, -v232, v36, v20
	v_fma_f32 v21, -v236, v36, v21
	v_fma_f32 v24, -v144, v36, v24
	v_fma_f32 v25, -v152, v36, v25
	v_fma_f32 v20, -v233, v37, v20
	ds_read_b128 v[230:233], v109 offset:15440
	v_fma_f32 v21, -v237, v37, v21
	ds_read_b128 v[234:237], v109 offset:15696
	v_fma_f32 v24, -v145, v37, v24
	ds_read_b128 v[142:145], v109 offset:15952
	v_fma_f32 v25, -v153, v37, v25
	ds_read_b128 v[150:153], v109 offset:16208
	s_waitcnt lgkmcnt(4)
	v_fma_f32 v20, -v220, v40, v20
	v_fma_f32 v21, -v158, v40, v21
	v_fma_f32 v24, -v154, v40, v24
	v_fma_f32 v25, -v146, v40, v25
	v_fma_f32 v20, -v221, v41, v20
	v_fma_f32 v21, -v159, v41, v21
	v_fma_f32 v24, -v155, v41, v24
	v_fma_f32 v25, -v147, v41, v25
	v_fma_f32 v20, -v222, v44, v20
	v_fma_f32 v21, -v160, v44, v21
	v_fma_f32 v24, -v156, v44, v24
	v_fma_f32 v25, -v148, v44, v25
	v_fma_f32 v20, -v223, v45, v20
	ds_read_b128 v[220:223], v109 offset:15456
	v_fma_f32 v21, -v161, v45, v21
	ds_read_b128 v[158:161], v109 offset:15712
	v_fma_f32 v24, -v157, v45, v24
	ds_read_b128 v[154:157], v109 offset:15968
	v_fma_f32 v25, -v149, v45, v25
	ds_read_b128 v[146:149], v109 offset:16224
	s_waitcnt lgkmcnt(4)
	v_fma_f32 v20, -v230, v50, v20
	v_fma_f32 v21, -v234, v50, v21
	v_fma_f32 v24, -v142, v50, v24
	v_fma_f32 v25, -v150, v50, v25
	v_fma_f32 v20, -v231, v51, v20
	v_fma_f32 v21, -v235, v51, v21
	v_fma_f32 v24, -v143, v51, v24
	v_fma_f32 v25, -v151, v51, v25
	v_fma_f32 v20, -v232, v54, v20
	v_fma_f32 v21, -v236, v54, v21
	v_fma_f32 v24, -v144, v54, v24
	v_fma_f32 v25, -v152, v54, v25
	v_fma_f32 v20, -v233, v55, v20
	ds_read_b128 v[230:233], v109 offset:15472
	v_fma_f32 v21, -v237, v55, v21
	ds_read_b128 v[234:237], v109 offset:15728
	v_fma_f32 v24, -v145, v55, v24
	ds_read_b128 v[142:145], v109 offset:15984
	v_fma_f32 v25, -v153, v55, v25
	ds_read_b128 v[150:153], v109 offset:16240
	s_waitcnt lgkmcnt(4)
	v_fma_f32 v20, -v220, v60, v20
	v_fma_f32 v21, -v158, v60, v21
	v_fma_f32 v24, -v154, v60, v24
	v_fma_f32 v25, -v146, v60, v25
	v_fma_f32 v20, -v221, v61, v20
	v_fma_f32 v21, -v159, v61, v21
	v_fma_f32 v24, -v155, v61, v24
	v_fma_f32 v25, -v147, v61, v25
	v_fma_f32 v20, -v222, v64, v20
	v_fma_f32 v21, -v160, v64, v21
	v_fma_f32 v24, -v156, v64, v24
	v_fma_f32 v25, -v148, v64, v25
	v_fma_f32 v20, -v223, v65, v20
	ds_read_b128 v[220:223], v109 offset:15488
	v_fma_f32 v21, -v161, v65, v21
	ds_read_b128 v[158:161], v109 offset:15744
	v_fma_f32 v24, -v157, v65, v24
	ds_read_b128 v[154:157], v109 offset:16000
	v_fma_f32 v25, -v149, v65, v25
	ds_read_b128 v[146:149], v109 offset:16256
	s_waitcnt lgkmcnt(4)
	v_fma_f32 v20, -v230, v70, v20
	v_fma_f32 v21, -v234, v70, v21
	v_fma_f32 v24, -v142, v70, v24
	v_fma_f32 v25, -v150, v70, v25
	v_fma_f32 v20, -v231, v71, v20
	v_fma_f32 v21, -v235, v71, v21
	v_fma_f32 v24, -v143, v71, v24
	v_fma_f32 v25, -v151, v71, v25
	v_fma_f32 v20, -v232, v112, v20
	v_fma_f32 v21, -v236, v112, v21
	v_fma_f32 v24, -v144, v112, v24
	v_fma_f32 v25, -v152, v112, v25
	v_fma_f32 v20, -v233, v113, v20
	ds_read_b128 v[230:233], v109 offset:15504
	v_fma_f32 v21, -v237, v113, v21
	ds_read_b128 v[234:237], v109 offset:15760
	v_fma_f32 v24, -v145, v113, v24
	ds_read_b128 v[142:145], v109 offset:16016
	v_fma_f32 v25, -v153, v113, v25
	ds_read_b128 v[150:153], v109 offset:16272
	s_waitcnt lgkmcnt(4)
	v_fma_f32 v20, -v220, v116, v20
	v_fma_f32 v21, -v158, v116, v21
	v_fma_f32 v24, -v154, v116, v24
	v_fma_f32 v25, -v146, v116, v25
	v_fma_f32 v20, -v221, v117, v20
	v_fma_f32 v21, -v159, v117, v21
	v_fma_f32 v24, -v155, v117, v24
	v_fma_f32 v25, -v147, v117, v25
	v_fma_f32 v20, -v222, v122, v20
	v_fma_f32 v21, -v160, v122, v21
	v_fma_f32 v24, -v156, v122, v24
	v_fma_f32 v25, -v148, v122, v25
	v_fma_f32 v20, -v223, v123, v20
	ds_read_b128 v[220:223], v109 offset:15520
	v_fma_f32 v21, -v161, v123, v21
	ds_read_b128 v[158:161], v109 offset:15776
	v_fma_f32 v24, -v157, v123, v24
	ds_read_b128 v[154:157], v109 offset:16032
	v_fma_f32 v25, -v149, v123, v25
	ds_read_b128 v[146:149], v109 offset:16288
	s_waitcnt lgkmcnt(4)
	v_fma_f32 v20, -v230, v128, v20
	v_fma_f32 v21, -v234, v128, v21
	v_fma_f32 v24, -v142, v128, v24
	v_fma_f32 v25, -v150, v128, v25
	v_fma_f32 v20, -v231, v129, v20
	v_fma_f32 v21, -v235, v129, v21
	v_fma_f32 v24, -v143, v129, v24
	v_fma_f32 v25, -v151, v129, v25
	v_fma_f32 v20, -v232, v134, v20
	v_fma_f32 v21, -v236, v134, v21
	v_fma_f32 v24, -v144, v134, v24
	v_fma_f32 v25, -v152, v134, v25
	v_fma_f32 v20, -v233, v135, v20
	ds_read_b128 v[230:233], v109 offset:15536
	v_fma_f32 v21, -v237, v135, v21
	ds_read_b128 v[234:237], v109 offset:15792
	v_fma_f32 v24, -v145, v135, v24
	ds_read_b128 v[142:145], v109 offset:16048
	v_fma_f32 v25, -v153, v135, v25
	ds_read_b128 v[150:153], v109 offset:16304
	s_waitcnt lgkmcnt(4)
; #define LAS __attribute__((address_space(3)))
; __device__ __forceinline__ void gdn_local_unit(LAS unsigned char* lds, const GdnP& P, int unit, const int tid, const int pf) {
;     ...
;         for (int c = 1; c < 64; ++c) { f32x2 sp = (f32x2){sol2[c >> 1][c & 1], 0.f};
; #pragma unroll
;             for (int jb = 0; jb <= (c - 1) / 4; ++jb) { const f32x4 m4 = *(const LAS f32x4*)(Ms + c * 64 + 4 * jb);
;                 sp -= (f32x2){m4.x, m4.y} * sol2[2 * jb]; sp -= (f32x2){m4.z, m4.w} * sol2[2 * jb + 1]; }
;             sol2[c >> 1][c & 1] = sp.x + sp.y; }
	v_fma_f32 v20, -v220, v140, v20
	v_fma_f32 v21, -v158, v140, v21
	v_fma_f32 v24, -v154, v140, v24
	v_fma_f32 v25, -v146, v140, v25
	v_fma_f32 v20, -v221, v141, v20
	v_fma_f32 v21, -v159, v141, v21
	v_fma_f32 v24, -v155, v141, v24
	v_fma_f32 v25, -v147, v141, v25
	v_fma_f32 v20, -v222, v138, v20
	v_fma_f32 v21, -v160, v138, v21
	v_fma_f32 v24, -v156, v138, v24
	v_fma_f32 v25, -v148, v138, v25
	v_fma_f32 v20, -v223, v139, v20
	ds_read_b128 v[220:223], v109 offset:15552
	v_fma_f32 v21, -v161, v139, v21
	ds_read_b128 v[158:161], v109 offset:15808
	v_fma_f32 v24, -v157, v139, v24
	ds_read_b128 v[154:157], v109 offset:16064
	v_fma_f32 v25, -v149, v139, v25
	ds_read_b128 v[146:149], v109 offset:16320
	s_waitcnt lgkmcnt(4)
	v_fma_f32 v20, -v230, v132, v20
	v_fma_f32 v21, -v234, v132, v21
	v_fma_f32 v24, -v142, v132, v24
	v_fma_f32 v25, -v150, v132, v25
	v_fma_f32 v20, -v231, v133, v20
	v_fma_f32 v21, -v235, v133, v21
	v_fma_f32 v24, -v143, v133, v24
	v_fma_f32 v25, -v151, v133, v25
	v_fma_f32 v20, -v232, v124, v20
	v_fma_f32 v21, -v236, v124, v21
	v_fma_f32 v24, -v144, v124, v24
	v_fma_f32 v25, -v152, v124, v25
	v_fma_f32 v20, -v233, v125, v20
	ds_read_b128 v[230:233], v109 offset:15568
	v_fma_f32 v21, -v237, v125, v21
	ds_read_b128 v[234:237], v109 offset:15824
	v_fma_f32 v24, -v145, v125, v24
	ds_read_b128 v[142:145], v109 offset:16080
	v_fma_f32 v25, -v153, v125, v25
	ds_read_b128 v[150:153], v109 offset:16336
	s_waitcnt lgkmcnt(4)
	v_fma_f32 v20, -v220, v118, v20
	v_fma_f32 v21, -v158, v118, v21
	v_fma_f32 v24, -v154, v118, v24
	v_fma_f32 v25, -v146, v118, v25
	v_fma_f32 v20, -v221, v119, v20
	v_fma_f32 v21, -v159, v119, v21
	v_fma_f32 v24, -v155, v119, v24
	v_fma_f32 v25, -v147, v119, v25
	v_fma_f32 v20, -v222, v74, v20
	v_fma_f32 v21, -v160, v74, v21
	v_fma_f32 v24, -v156, v74, v24
	v_fma_f32 v25, -v148, v74, v25
	v_fma_f32 v20, -v223, v75, v20
	ds_read_b128 v[220:223], v109 offset:15584
	v_fma_f32 v21, -v161, v75, v21
	ds_read_b128 v[158:161], v109 offset:15840
	v_fma_f32 v24, -v157, v75, v24
	ds_read_b128 v[154:157], v109 offset:16096
	v_fma_f32 v25, -v149, v75, v25
	ds_read_b128 v[146:149], v109 offset:16352
	s_waitcnt lgkmcnt(4)
	v_fma_f32 v20, -v230, v66, v20
	v_fma_f32 v21, -v234, v66, v21
	v_fma_f32 v24, -v142, v66, v24
	v_fma_f32 v25, -v150, v66, v25
	v_fma_f32 v20, -v231, v67, v20
	v_fma_f32 v21, -v235, v67, v21
	v_fma_f32 v24, -v143, v67, v24
	v_fma_f32 v25, -v151, v67, v25
	v_fma_f32 v20, -v232, v56, v20
	v_fma_f32 v21, -v236, v56, v21
	v_fma_f32 v24, -v144, v56, v24
	v_fma_f32 v25, -v152, v56, v25
	v_fma_f32 v20, -v233, v57, v20
	ds_read_b128 v[230:233], v109 offset:15856
	v_fma_f32 v21, -v237, v57, v21
	ds_read_b128 v[234:237], v109 offset:16112
	v_fma_f32 v24, -v145, v57, v24
	ds_read_b128 v[142:145], v109 offset:16368
	v_fma_f32 v25, -v153, v57, v25
	s_waitcnt lgkmcnt(3)
	v_fma_f32 v20, -v220, v46, v20
	v_fma_f32 v21, -v158, v46, v21
	v_fma_f32 v24, -v154, v46, v24
	v_fma_f32 v25, -v146, v46, v25
	v_fma_f32 v20, -v221, v47, v20
	v_fma_f32 v21, -v159, v47, v21
	v_fma_f32 v24, -v155, v47, v24
	v_fma_f32 v25, -v147, v47, v25
	v_fma_f32 v20, -v222, v32, v20
	v_fma_f32 v21, -v160, v32, v21
	v_fma_f32 v24, -v156, v32, v24
	v_fma_f32 v25, -v148, v32, v25
	v_fma_f32 v12, -v223, v33, v20
	v_fma_f32 v21, -v161, v33, v21
	v_fma_f32 v24, -v157, v33, v24
	v_fma_f32 v25, -v149, v33, v25
	s_waitcnt lgkmcnt(0)
	v_fma_f32 v13, -v230, v12, v21
	v_fma_f32 v24, -v234, v12, v24
	v_fma_f32 v25, -v142, v12, v25
	v_fma_f32 v2, -v235, v13, v24
	v_fma_f32 v25, -v143, v13, v25
	v_fma_f32 v3, -v144, v2, v25
	s_and_saveexec_b64 s[0:1], s[8:9]
	s_xor_b64 s[0:1], exec, s[0:1]
	s_cbranch_execz .LBB0_1027
; #define LAS __attribute__((address_space(3)))
; __device__ __forceinline__ unsigned f2bf(float f) { return pk2(f, 0.f) & 0xffffu; }
; __device__ __forceinline__ void gdn_local_unit(LAS unsigned char* lds, const GdnP& P, int unit, const int tid, const int pf) {
;     ...
;         if (col < 128) {
; #pragma unroll
;             for (int t = 0; t < 64; ++t) Vs[t * 128 + col] = sol2[t >> 1][t & 1];
;         } else {
; #pragma unroll
;             for (int t = 0; t < 64; ++t) *(LAS bf16_t*)(lds + GL_QB + t * 272 + (col - 128) * 2) = (bf16_t)f2bf(sol2[t >> 1][t & 1]);
;         }
	v_cvt_pk_bf16_f32 v100, v0, v0
	ds_write_b16 v200, v100
	v_cvt_pk_bf16_f32 v100, v1, v1
	ds_write_b16 v199, v100 offset:16
	v_cvt_pk_bf16_f32 v100, v8, v8
	ds_write_b16 v199, v100 offset:288
	v_cvt_pk_bf16_f32 v100, v9, v9
	ds_write_b16 v199, v100 offset:560
	v_cvt_pk_bf16_f32 v100, v14, v14
	ds_write_b16 v199, v100 offset:832
	v_cvt_pk_bf16_f32 v100, v15, v15
	ds_write_b16 v199, v100 offset:1104
	v_cvt_pk_bf16_f32 v100, v18, v18
	ds_write_b16 v199, v100 offset:1376
	v_cvt_pk_bf16_f32 v100, v19, v19
	ds_write_b16 v199, v100 offset:1648
	v_cvt_pk_bf16_f32 v100, v22, v22
	ds_write_b16 v199, v100 offset:1920
	v_cvt_pk_bf16_f32 v100, v23, v23
	ds_write_b16 v199, v100 offset:2192
	v_cvt_pk_bf16_f32 v100, v26, v26
	ds_write_b16 v199, v100 offset:2464
	v_cvt_pk_bf16_f32 v100, v27, v27
	ds_write_b16 v199, v100 offset:2736
	v_cvt_pk_bf16_f32 v100, v30, v30
	ds_write_b16 v199, v100 offset:3008
	v_cvt_pk_bf16_f32 v100, v31, v31
	ds_write_b16 v199, v100 offset:3280
	v_cvt_pk_bf16_f32 v100, v36, v36
	ds_write_b16 v199, v100 offset:3552
	v_cvt_pk_bf16_f32 v100, v37, v37
	ds_write_b16 v199, v100 offset:3824
	v_cvt_pk_bf16_f32 v100, v40, v40
	ds_write_b16 v199, v100 offset:4096
	v_cvt_pk_bf16_f32 v100, v41, v41
	ds_write_b16 v199, v100 offset:4368
	v_cvt_pk_bf16_f32 v100, v44, v44
	ds_write_b16 v199, v100 offset:4640
	v_cvt_pk_bf16_f32 v100, v45, v45
	ds_write_b16 v199, v100 offset:4912
	v_cvt_pk_bf16_f32 v100, v50, v50
	ds_write_b16 v199, v100 offset:5184
	v_cvt_pk_bf16_f32 v100, v51, v51
	ds_write_b16 v199, v100 offset:5456
	v_cvt_pk_bf16_f32 v100, v54, v54
	ds_write_b16 v199, v100 offset:5728
	v_cvt_pk_bf16_f32 v100, v55, v55
	ds_write_b16 v199, v100 offset:6000
	v_cvt_pk_bf16_f32 v100, v60, v60
	ds_write_b16 v199, v100 offset:6272
	v_cvt_pk_bf16_f32 v100, v61, v61
	ds_write_b16 v199, v100 offset:6544
	v_cvt_pk_bf16_f32 v100, v64, v64
	ds_write_b16 v199, v100 offset:6816
	v_cvt_pk_bf16_f32 v100, v65, v65
	ds_write_b16 v199, v100 offset:7088
	v_cvt_pk_bf16_f32 v100, v70, v70
	ds_write_b16 v199, v100 offset:7360
	v_cvt_pk_bf16_f32 v100, v71, v71
	ds_write_b16 v199, v100 offset:7632
	v_cvt_pk_bf16_f32 v100, v112, v112
	ds_write_b16 v199, v100 offset:7904
	v_cvt_pk_bf16_f32 v100, v113, v113
	ds_write_b16 v199, v100 offset:8176
	v_cvt_pk_bf16_f32 v100, v116, v116
	ds_write_b16 v199, v100 offset:8448
	v_cvt_pk_bf16_f32 v100, v117, v117
	ds_write_b16 v199, v100 offset:8720
	v_cvt_pk_bf16_f32 v100, v122, v122
	ds_write_b16 v199, v100 offset:8992
	v_cvt_pk_bf16_f32 v100, v123, v123
	ds_write_b16 v199, v100 offset:9264
	v_cvt_pk_bf16_f32 v100, v128, v128
	ds_write_b16 v199, v100 offset:9536
	v_cvt_pk_bf16_f32 v100, v129, v129
	ds_write_b16 v199, v100 offset:9808
	v_cvt_pk_bf16_f32 v100, v134, v134
	ds_write_b16 v199, v100 offset:10080
	v_cvt_pk_bf16_f32 v100, v135, v135
	ds_write_b16 v199, v100 offset:10352
	v_cvt_pk_bf16_f32 v100, v140, v140
	ds_write_b16 v199, v100 offset:10624
	v_cvt_pk_bf16_f32 v100, v141, v141
	ds_write_b16 v199, v100 offset:10896
	v_cvt_pk_bf16_f32 v100, v138, v138
	ds_write_b16 v199, v100 offset:11168
	v_cvt_pk_bf16_f32 v100, v139, v139
	ds_write_b16 v199, v100 offset:11440
	v_cvt_pk_bf16_f32 v100, v132, v132
	ds_write_b16 v199, v100 offset:11712
	v_cvt_pk_bf16_f32 v100, v133, v133
	ds_write_b16 v199, v100 offset:11984
	v_cvt_pk_bf16_f32 v100, v124, v124
	ds_write_b16 v199, v100 offset:12256
	v_cvt_pk_bf16_f32 v100, v125, v125
	ds_write_b16 v199, v100 offset:12528
	v_cvt_pk_bf16_f32 v100, v118, v118
	ds_write_b16 v199, v100 offset:12800
	v_cvt_pk_bf16_f32 v100, v119, v119
	ds_write_b16 v199, v100 offset:13072
	v_cvt_pk_bf16_f32 v100, v74, v74
	ds_write_b16 v199, v100 offset:13344
	v_cvt_pk_bf16_f32 v100, v75, v75
	ds_write_b16 v199, v100 offset:13616
	v_cvt_pk_bf16_f32 v100, v66, v66
	ds_write_b16 v199, v100 offset:13888
	v_cvt_pk_bf16_f32 v100, v67, v67
	ds_write_b16 v199, v100 offset:14160
	v_cvt_pk_bf16_f32 v100, v56, v56
	ds_write_b16 v199, v100 offset:14432
	v_cvt_pk_bf16_f32 v100, v57, v57
	ds_write_b16 v199, v100 offset:14704
	v_cvt_pk_bf16_f32 v100, v46, v46
	ds_write_b16 v199, v100 offset:14976
	v_cvt_pk_bf16_f32 v100, v47, v47
	ds_write_b16 v199, v100 offset:15248
	v_cvt_pk_bf16_f32 v100, v32, v32
	ds_write_b16 v199, v100 offset:15520
	v_cvt_pk_bf16_f32 v100, v33, v33
	ds_write_b16 v199, v100 offset:15792
	v_cvt_pk_bf16_f32 v100, v12, v12
	ds_write_b16 v199, v100 offset:16064
	v_cvt_pk_bf16_f32 v100, v13, v13
	ds_write_b16 v199, v100 offset:16336
	v_cvt_pk_bf16_f32 v100, v2, v2
	ds_write_b16 v199, v100 offset:16608
	v_cvt_pk_bf16_f32 v100, v3, v3
	ds_write_b16 v199, v100 offset:16880
.LBB0_1027:
	s_andn2_saveexec_b64 s[0:1], s[0:1]
	s_cbranch_execz .LBB0_1029
	ds_write2st64_b32 v111, v0, v1 offset1:2
	ds_write2st64_b32 v111, v8, v9 offset0:4 offset1:6
	ds_write2st64_b32 v111, v14, v15 offset0:8 offset1:10
	ds_write2st64_b32 v111, v18, v19 offset0:12 offset1:14
	ds_write2st64_b32 v111, v22, v23 offset0:16 offset1:18
	ds_write2st64_b32 v111, v26, v27 offset0:20 offset1:22
	ds_write2st64_b32 v111, v30, v31 offset0:24 offset1:26
	ds_write2st64_b32 v111, v36, v37 offset0:28 offset1:30
	ds_write2st64_b32 v111, v40, v41 offset0:32 offset1:34
	ds_write2st64_b32 v111, v44, v45 offset0:36 offset1:38
	ds_write2st64_b32 v111, v50, v51 offset0:40 offset1:42
	ds_write2st64_b32 v111, v54, v55 offset0:44 offset1:46
	ds_write2st64_b32 v111, v60, v61 offset0:48 offset1:50
	ds_write2st64_b32 v111, v64, v65 offset0:52 offset1:54
	ds_write2st64_b32 v111, v70, v71 offset0:56 offset1:58
	ds_write2st64_b32 v111, v112, v113 offset0:60 offset1:62
	ds_write2st64_b32 v111, v116, v117 offset0:64 offset1:66
	ds_write2st64_b32 v111, v122, v123 offset0:68 offset1:70
	ds_write2st64_b32 v111, v128, v129 offset0:72 offset1:74
	ds_write2st64_b32 v111, v134, v135 offset0:76 offset1:78
	ds_write2st64_b32 v111, v140, v141 offset0:80 offset1:82
	ds_write2st64_b32 v111, v138, v139 offset0:84 offset1:86
	ds_write2st64_b32 v111, v132, v133 offset0:88 offset1:90
	ds_write2st64_b32 v111, v124, v125 offset0:92 offset1:94
	ds_write2st64_b32 v111, v118, v119 offset0:96 offset1:98
	ds_write2st64_b32 v111, v74, v75 offset0:100 offset1:102
	ds_write2st64_b32 v111, v66, v67 offset0:104 offset1:106
	ds_write2st64_b32 v111, v56, v57 offset0:108 offset1:110
	ds_write2st64_b32 v111, v46, v47 offset0:112 offset1:114
	ds_write2st64_b32 v111, v32, v33 offset0:116 offset1:118
	ds_write2st64_b32 v111, v12, v13 offset0:120 offset1:122
	ds_write2st64_b32 v111, v2, v3 offset0:124 offset1:126
